# sample-row blocks + pipelined residual epilogues (P2 P6 P9 P11) + memory K/V projection GEMM moved from FFN1-down phase to workgroups 128.. of the token-mixer phase
# speedup vs baseline: 1.0075x; 1.0075x over previous
.LBB0_248:
	s_or_b64 exec, exec, s[6:7]
	s_waitcnt lgkmcnt(0)
	v_mov_b32_e32 v0, v206
	v_mov_b32_e32 v8, v206
	s_cmpk_lt_i32 s2, 0x404
	s_barrier
	s_cselect_b64 s[8:9], -1, 0
	v_lshrrev_b32_e32 v11, 6, v206
	v_and_b32_e32 v8, 63, v206
	s_load_dwordx2 s[96:97], s[0:1], 0x118
	v_readfirstlane_b32 s86, v11
	s_load_dwordx2 s[98:99], s[0:1], 0x8
	v_and_b32_e32 v9, 15, v8
	v_lshrrev_b32_e32 v10, 4, v8
	s_and_b32 s32, s86, 3
	s_lshr_b32 s101, s86, 2
	s_load_dwordx2 s[94:95], s[0:1], 0x110
	s_load_dwordx2 s[90:91], s[0:1], 0x0
	s_mov_b32 s87, s2
	v_lshlrev_b32_e32 v11, 4, v10
	s_mul_i32 s100, s101, 0xb00
	v_mov_b32_e32 v12, 0x1600
	v_mul_u32_u24_e32 v12, v9, v12
	v_mov_b32_e32 v14, 0x1600
	v_mul_u32_u24_e32 v14, v9, v14
	v_add_u32_e32 v12, v12, v11
	v_add_u32_e32 v14, v14, v11
	v_add_u32_e32 v12, s100, v12
	v_add_u32_e32 v14, s100, v14
	v_mov_b32_e32 v13, 0
	v_mov_b32_e32 v15, 0
	s_lshl_b32 s100, s32, 10
	s_add_u32 s100, s100, 0x20000
	v_lshlrev_b32_e32 v34, 4, v8
	v_add_u32_e32 v34, s100, v34
	s_lshl_b32 s100, s32, 8
	s_add_u32 s100, s100, 0x22000
	v_lshlrev_b32_e32 v35, 2, v8
	v_add_u32_e32 v35, s100, v35
	v_xor_b32_e32 v32, 16, v8
	v_lshlrev_b32_e32 v32, 2, v32
	v_xor_b32_e32 v33, 32, v8
	v_lshlrev_b32_e32 v33, 2, v33
	s_waitcnt lgkmcnt(0)

.LBB0_274:
	v_lshrrev_b32_e32 v132, 6, v206
	v_and_b32_e32 v143, 63, v206
	v_lshrrev_b32_e32 v142, 2, v132
	v_and_b32_e32 v132, 3, v132
	v_lshlrev_b32_e32 v142, 6, v142
	v_lshrrev_b32_e32 v214, 4, v143
	v_and_b32_e32 v215, 15, v143
	v_xor_b32_e32 v212, 16, v143
	v_xor_b32_e32 v213, 32, v143
	v_lshlrev_b32_e32 v212, 2, v212
	v_lshlrev_b32_e32 v213, 2, v213
	v_add_u32_e32 v142, v142, v215
	v_lshlrev_b32_e32 v143, 5, v132
	v_lshl_add_u32 v143, v214, 2, v143
	s_lshl_b32 vcc_lo, s24, 8
	v_add_u32_e32 v142, vcc_lo, v142
	s_lshl_b32 vcc_lo, s57, 8
	v_add_u32_e32 v143, vcc_lo, v143
	v_lshlrev_b32_e32 v148, 12, v142
	v_lshl_add_u32 v148, v143, 2, v148
	v_lshlrev_b32_e32 v149, 11, v142
	v_lshl_add_u32 v149, v143, 1, v149
	s_lshl_b32 vcc_lo, s57, 2
	v_add_u32_e32 v132, vcc_lo, v132
	v_lshlrev_b32_e32 v158, 6, v142
	v_lshl_add_u32 v158, v132, 2, v158
	s_mov_b32 s86, s90
	s_mov_b32 s87, s91
	s_mov_b32 s88, s94
	s_mov_b32 s89, s95
	s_add_u32 s92, s96, 0x9e00000
	s_addc_u32 s93, s97, 0
	s_add_u32 s100, s96, 0x4600000
	s_addc_u32 s101, s97, 0
	global_load_dwordx4 v[144:147], v148, s[86:87]
	global_load_dwordx4 v[160:163], v148, s[86:87] offset:64
	global_load_dwordx4 v[164:167], v148, s[86:87] offset:512
	global_load_dwordx4 v[168:171], v148, s[86:87] offset:576
	s_add_u32 s86, s86, 0x10000
	s_addc_u32 s87, s87, 0
	global_load_dwordx4 v[172:175], v148, s[86:87]
	global_load_dwordx4 v[176:179], v148, s[86:87] offset:64
	global_load_dwordx4 v[180:183], v148, s[86:87] offset:512
	global_load_dwordx4 v[184:187], v148, s[86:87] offset:576
	s_add_u32 s86, s86, 0x10000
	s_addc_u32 s87, s87, 0
	global_load_dwordx4 v[188:191], v148, s[86:87]
	global_load_dwordx4 v[192:195], v148, s[86:87] offset:64
	global_load_dwordx4 v[196:199], v148, s[86:87] offset:512
	global_load_dwordx4 v[200:203], v148, s[86:87] offset:576
	s_waitcnt vmcnt(11)
	v_fma_f32 v124, v124, 0.5, v144
	v_fma_f32 v125, v125, 0.5, v145
	v_fma_f32 v126, v126, 0.5, v146
	v_fma_f32 v127, v127, 0.5, v147
	global_store_dwordx4 v148, v[124:127], s[88:89]
	v_cvt_pk_bf16_f32 v144, v124, v125
	v_cvt_pk_bf16_f32 v145, v126, v127
	global_store_dwordx2 v149, v[144:145], s[92:93]
	v_mul_f32_e32 v159, v124, v124
	v_fmac_f32_e32 v159, v125, v125
	v_fmac_f32_e32 v159, v126, v126
	v_fmac_f32_e32 v159, v127, v127
	s_add_u32 s86, s86, 0x10000
	s_addc_u32 s87, s87, 0
	global_load_dwordx4 v[144:147], v148, s[86:87]
	s_waitcnt vmcnt(13)
	v_fma_f32 v120, v120, 0.5, v160
	v_fma_f32 v121, v121, 0.5, v161
	v_fma_f32 v122, v122, 0.5, v162
	v_fma_f32 v123, v123, 0.5, v163
	global_store_dwordx4 v148, v[120:123], s[88:89] offset:64
	v_cvt_pk_bf16_f32 v160, v120, v121
	v_cvt_pk_bf16_f32 v161, v122, v123
	global_store_dwordx2 v149, v[160:161], s[92:93] offset:32
	v_fmac_f32_e32 v159, v120, v120
	v_fmac_f32_e32 v159, v121, v121
	v_fmac_f32_e32 v159, v122, v122
	v_fmac_f32_e32 v159, v123, v123
	global_load_dwordx4 v[160:163], v148, s[86:87] offset:64
	s_waitcnt vmcnt(15)
	v_fma_f32 v116, v116, 0.5, v164
	v_fma_f32 v117, v117, 0.5, v165
	v_fma_f32 v118, v118, 0.5, v166
	v_fma_f32 v119, v119, 0.5, v167
	global_store_dwordx4 v148, v[116:119], s[88:89] offset:512
	v_cvt_pk_bf16_f32 v164, v116, v117
	v_cvt_pk_bf16_f32 v165, v118, v119
	global_store_dwordx2 v149, v[164:165], s[92:93] offset:256
	v_fmac_f32_e32 v159, v116, v116
	v_fmac_f32_e32 v159, v117, v117
	v_fmac_f32_e32 v159, v118, v118
	v_fmac_f32_e32 v159, v119, v119
	global_load_dwordx4 v[164:167], v148, s[86:87] offset:512
	s_waitcnt vmcnt(17)
	v_fma_f32 v112, v112, 0.5, v168
	v_fma_f32 v113, v113, 0.5, v169
	v_fma_f32 v114, v114, 0.5, v170
	v_fma_f32 v115, v115, 0.5, v171
	global_store_dwordx4 v148, v[112:115], s[88:89] offset:576
	v_cvt_pk_bf16_f32 v168, v112, v113
	v_cvt_pk_bf16_f32 v169, v114, v115
	global_store_dwordx2 v149, v[168:169], s[92:93] offset:288
	v_fmac_f32_e32 v159, v112, v112
	v_fmac_f32_e32 v159, v113, v113
	v_fmac_f32_e32 v159, v114, v114
	v_fmac_f32_e32 v159, v115, v115
	global_load_dwordx4 v[168:171], v148, s[86:87] offset:576
	s_nop 0
	ds_bpermute_b32 v215, v212, v159
	s_waitcnt lgkmcnt(0)
	v_add_f32_e32 v159, v159, v215
	s_nop 0
	ds_bpermute_b32 v215, v213, v159
	s_waitcnt lgkmcnt(0)
	v_add_f32_e32 v159, v159, v215
	v_cmp_eq_u32_e32 vcc, 0, v214
	s_and_saveexec_b64 s[98:99], vcc
	global_store_dword v158, v159, s[100:101]
	s_mov_b64 exec, s[98:99]
	s_add_u32 s88, s88, 0x10000
	s_addc_u32 s89, s89, 0
	s_add_u32 s92, s92, 0x8000
	s_addc_u32 s93, s93, 0
	s_add_u32 s100, s100, 0x400
	s_addc_u32 s101, s101, 0
	s_waitcnt vmcnt(20)
	v_fma_f32 v108, v108, 0.5, v172
	v_fma_f32 v109, v109, 0.5, v173
	v_fma_f32 v110, v110, 0.5, v174
	v_fma_f32 v111, v111, 0.5, v175
	global_store_dwordx4 v148, v[108:111], s[88:89]
	v_cvt_pk_bf16_f32 v172, v108, v109
	v_cvt_pk_bf16_f32 v173, v110, v111
	global_store_dwordx2 v149, v[172:173], s[92:93]
	v_mul_f32_e32 v159, v108, v108
	v_fmac_f32_e32 v159, v109, v109
	v_fmac_f32_e32 v159, v110, v110
	v_fmac_f32_e32 v159, v111, v111
	s_add_u32 s86, s86, 0x50000
	s_addc_u32 s87, s87, 0
	global_load_dwordx4 v[172:175], v148, s[86:87]
	s_waitcnt vmcnt(22)
	v_fma_f32 v104, v104, 0.5, v176
	v_fma_f32 v105, v105, 0.5, v177
	v_fma_f32 v106, v106, 0.5, v178
	v_fma_f32 v107, v107, 0.5, v179
	global_store_dwordx4 v148, v[104:107], s[88:89] offset:64
	v_cvt_pk_bf16_f32 v176, v104, v105
	v_cvt_pk_bf16_f32 v177, v106, v107
	global_store_dwordx2 v149, v[176:177], s[92:93] offset:32
	v_fmac_f32_e32 v159, v104, v104
	v_fmac_f32_e32 v159, v105, v105
	v_fmac_f32_e32 v159, v106, v106
	v_fmac_f32_e32 v159, v107, v107
	global_load_dwordx4 v[176:179], v148, s[86:87] offset:64
	s_waitcnt vmcnt(24)
	v_fma_f32 v100, v100, 0.5, v180
	v_fma_f32 v101, v101, 0.5, v181
	v_fma_f32 v102, v102, 0.5, v182
	v_fma_f32 v103, v103, 0.5, v183
	global_store_dwordx4 v148, v[100:103], s[88:89] offset:512
	v_cvt_pk_bf16_f32 v180, v100, v101
	v_cvt_pk_bf16_f32 v181, v102, v103
	global_store_dwordx2 v149, v[180:181], s[92:93] offset:256
	v_fmac_f32_e32 v159, v100, v100
	v_fmac_f32_e32 v159, v101, v101
	v_fmac_f32_e32 v159, v102, v102
	v_fmac_f32_e32 v159, v103, v103
	global_load_dwordx4 v[180:183], v148, s[86:87] offset:512
	s_waitcnt vmcnt(26)
	v_fma_f32 v96, v96, 0.5, v184
	v_fma_f32 v97, v97, 0.5, v185
	v_fma_f32 v98, v98, 0.5, v186
	v_fma_f32 v99, v99, 0.5, v187
	global_store_dwordx4 v148, v[96:99], s[88:89] offset:576
	v_cvt_pk_bf16_f32 v184, v96, v97
	v_cvt_pk_bf16_f32 v185, v98, v99
	global_store_dwordx2 v149, v[184:185], s[92:93] offset:288
	v_fmac_f32_e32 v159, v96, v96
	v_fmac_f32_e32 v159, v97, v97
	v_fmac_f32_e32 v159, v98, v98
	v_fmac_f32_e32 v159, v99, v99
	global_load_dwordx4 v[184:187], v148, s[86:87] offset:576
	s_nop 0
	ds_bpermute_b32 v215, v212, v159
	s_waitcnt lgkmcnt(0)
	v_add_f32_e32 v159, v159, v215
	s_nop 0
	ds_bpermute_b32 v215, v213, v159
	s_waitcnt lgkmcnt(0)
	v_add_f32_e32 v159, v159, v215
	v_cmp_eq_u32_e32 vcc, 0, v214
	s_and_saveexec_b64 s[98:99], vcc
	global_store_dword v158, v159, s[100:101]
	s_mov_b64 exec, s[98:99]
	s_add_u32 s88, s88, 0x10000
	s_addc_u32 s89, s89, 0
	s_add_u32 s92, s92, 0x8000
	s_addc_u32 s93, s93, 0
	s_add_u32 s100, s100, 0x400
	s_addc_u32 s101, s101, 0
	s_waitcnt vmcnt(29)
	v_fma_f32 v92, v92, 0.5, v188
	v_fma_f32 v93, v93, 0.5, v189
	v_fma_f32 v94, v94, 0.5, v190
	v_fma_f32 v95, v95, 0.5, v191
	global_store_dwordx4 v148, v[92:95], s[88:89]
	v_cvt_pk_bf16_f32 v188, v92, v93
	v_cvt_pk_bf16_f32 v189, v94, v95
	global_store_dwordx2 v149, v[188:189], s[92:93]
	v_mul_f32_e32 v159, v92, v92
	v_fmac_f32_e32 v159, v93, v93
	v_fmac_f32_e32 v159, v94, v94
	v_fmac_f32_e32 v159, v95, v95
	s_add_u32 s86, s86, 0x10000
	s_addc_u32 s87, s87, 0
	global_load_dwordx4 v[188:191], v148, s[86:87]
	s_waitcnt vmcnt(31)
	v_fma_f32 v88, v88, 0.5, v192
	v_fma_f32 v89, v89, 0.5, v193
	v_fma_f32 v90, v90, 0.5, v194
	v_fma_f32 v91, v91, 0.5, v195
	global_store_dwordx4 v148, v[88:91], s[88:89] offset:64
	v_cvt_pk_bf16_f32 v192, v88, v89
	v_cvt_pk_bf16_f32 v193, v90, v91
	global_store_dwordx2 v149, v[192:193], s[92:93] offset:32
	v_fmac_f32_e32 v159, v88, v88
	v_fmac_f32_e32 v159, v89, v89
	v_fmac_f32_e32 v159, v90, v90
	v_fmac_f32_e32 v159, v91, v91
	global_load_dwordx4 v[192:195], v148, s[86:87] offset:64
	s_waitcnt vmcnt(33)
	v_fma_f32 v84, v84, 0.5, v196
	v_fma_f32 v85, v85, 0.5, v197
	v_fma_f32 v86, v86, 0.5, v198
	v_fma_f32 v87, v87, 0.5, v199
	global_store_dwordx4 v148, v[84:87], s[88:89] offset:512
	v_cvt_pk_bf16_f32 v196, v84, v85
	v_cvt_pk_bf16_f32 v197, v86, v87
	global_store_dwordx2 v149, v[196:197], s[92:93] offset:256
	v_fmac_f32_e32 v159, v84, v84
	v_fmac_f32_e32 v159, v85, v85
	v_fmac_f32_e32 v159, v86, v86
	v_fmac_f32_e32 v159, v87, v87
	global_load_dwordx4 v[196:199], v148, s[86:87] offset:512
	s_waitcnt vmcnt(35)
	v_fma_f32 v80, v80, 0.5, v200
	v_fma_f32 v81, v81, 0.5, v201
	v_fma_f32 v82, v82, 0.5, v202
	v_fma_f32 v83, v83, 0.5, v203
	global_store_dwordx4 v148, v[80:83], s[88:89] offset:576
	v_cvt_pk_bf16_f32 v200, v80, v81
	v_cvt_pk_bf16_f32 v201, v82, v83
	global_store_dwordx2 v149, v[200:201], s[92:93] offset:288
	v_fmac_f32_e32 v159, v80, v80
	v_fmac_f32_e32 v159, v81, v81
	v_fmac_f32_e32 v159, v82, v82
	v_fmac_f32_e32 v159, v83, v83
	global_load_dwordx4 v[200:203], v148, s[86:87] offset:576
	s_nop 0
	ds_bpermute_b32 v215, v212, v159
	s_waitcnt lgkmcnt(0)
	v_add_f32_e32 v159, v159, v215
	s_nop 0
	ds_bpermute_b32 v215, v213, v159
	s_waitcnt lgkmcnt(0)
	v_add_f32_e32 v159, v159, v215
	v_cmp_eq_u32_e32 vcc, 0, v214
	s_and_saveexec_b64 s[98:99], vcc
	global_store_dword v158, v159, s[100:101]
	s_mov_b64 exec, s[98:99]
	s_add_u32 s88, s88, 0x10000
	s_addc_u32 s89, s89, 0
	s_add_u32 s92, s92, 0x8000
	s_addc_u32 s93, s93, 0
	s_add_u32 s100, s100, 0x400
	s_addc_u32 s101, s101, 0
	s_waitcnt vmcnt(36)
	v_fma_f32 v76, v76, 0.5, v144
	v_fma_f32 v77, v77, 0.5, v145
	v_fma_f32 v78, v78, 0.5, v146
	v_fma_f32 v79, v79, 0.5, v147
	global_store_dwordx4 v148, v[76:79], s[88:89]
	v_cvt_pk_bf16_f32 v144, v76, v77
	v_cvt_pk_bf16_f32 v145, v78, v79
	global_store_dwordx2 v149, v[144:145], s[92:93]
	v_mul_f32_e32 v159, v76, v76
	v_fmac_f32_e32 v159, v77, v77
	v_fmac_f32_e32 v159, v78, v78
	v_fmac_f32_e32 v159, v79, v79
	s_add_u32 s86, s86, 0x10000
	s_addc_u32 s87, s87, 0
	global_load_dwordx4 v[144:147], v148, s[86:87]
	s_waitcnt vmcnt(36)
	v_fma_f32 v72, v72, 0.5, v160
	v_fma_f32 v73, v73, 0.5, v161
	v_fma_f32 v74, v74, 0.5, v162
	v_fma_f32 v75, v75, 0.5, v163
	global_store_dwordx4 v148, v[72:75], s[88:89] offset:64
	v_cvt_pk_bf16_f32 v160, v72, v73
	v_cvt_pk_bf16_f32 v161, v74, v75
	global_store_dwordx2 v149, v[160:161], s[92:93] offset:32
	v_fmac_f32_e32 v159, v72, v72
	v_fmac_f32_e32 v159, v73, v73
	v_fmac_f32_e32 v159, v74, v74
	v_fmac_f32_e32 v159, v75, v75
	global_load_dwordx4 v[160:163], v148, s[86:87] offset:64
	s_waitcnt vmcnt(36)
	v_fma_f32 v68, v68, 0.5, v164
	v_fma_f32 v69, v69, 0.5, v165
	v_fma_f32 v70, v70, 0.5, v166
	v_fma_f32 v71, v71, 0.5, v167
	global_store_dwordx4 v148, v[68:71], s[88:89] offset:512
	v_cvt_pk_bf16_f32 v164, v68, v69
	v_cvt_pk_bf16_f32 v165, v70, v71
	global_store_dwordx2 v149, v[164:165], s[92:93] offset:256
	v_fmac_f32_e32 v159, v68, v68
	v_fmac_f32_e32 v159, v69, v69
	v_fmac_f32_e32 v159, v70, v70
	v_fmac_f32_e32 v159, v71, v71
	global_load_dwordx4 v[164:167], v148, s[86:87] offset:512
	s_waitcnt vmcnt(36)
	v_fma_f32 v64, v64, 0.5, v168
	v_fma_f32 v65, v65, 0.5, v169
	v_fma_f32 v66, v66, 0.5, v170
	v_fma_f32 v67, v67, 0.5, v171
	global_store_dwordx4 v148, v[64:67], s[88:89] offset:576
	v_cvt_pk_bf16_f32 v168, v64, v65
	v_cvt_pk_bf16_f32 v169, v66, v67
	global_store_dwordx2 v149, v[168:169], s[92:93] offset:288
	v_fmac_f32_e32 v159, v64, v64
	v_fmac_f32_e32 v159, v65, v65
	v_fmac_f32_e32 v159, v66, v66
	v_fmac_f32_e32 v159, v67, v67
	global_load_dwordx4 v[168:171], v148, s[86:87] offset:576
	s_nop 0
	ds_bpermute_b32 v215, v212, v159
	s_waitcnt lgkmcnt(0)
	v_add_f32_e32 v159, v159, v215
	s_nop 0
	ds_bpermute_b32 v215, v213, v159
	s_waitcnt lgkmcnt(0)
	v_add_f32_e32 v159, v159, v215
	v_cmp_eq_u32_e32 vcc, 0, v214
	s_and_saveexec_b64 s[98:99], vcc
	global_store_dword v158, v159, s[100:101]
	s_mov_b64 exec, s[98:99]
	s_add_u32 s88, s88, 0x50000
	s_addc_u32 s89, s89, 0
	s_add_u32 s92, s92, 0x28000
	s_addc_u32 s93, s93, 0
	s_add_u32 s100, s100, 0x1400
	s_addc_u32 s101, s101, 0
	s_waitcnt vmcnt(36)
	v_fma_f32 v60, v60, 0.5, v172
	v_fma_f32 v61, v61, 0.5, v173
	v_fma_f32 v62, v62, 0.5, v174
	v_fma_f32 v63, v63, 0.5, v175
	global_store_dwordx4 v148, v[60:63], s[88:89]
	v_cvt_pk_bf16_f32 v172, v60, v61
	v_cvt_pk_bf16_f32 v173, v62, v63
	global_store_dwordx2 v149, v[172:173], s[92:93]
	v_mul_f32_e32 v159, v60, v60
	v_fmac_f32_e32 v159, v61, v61
	v_fmac_f32_e32 v159, v62, v62
	v_fmac_f32_e32 v159, v63, v63
	s_add_u32 s86, s86, 0x10000
	s_addc_u32 s87, s87, 0
	global_load_dwordx4 v[172:175], v148, s[86:87]
	s_waitcnt vmcnt(36)
	v_fma_f32 v56, v56, 0.5, v176
	v_fma_f32 v57, v57, 0.5, v177
	v_fma_f32 v58, v58, 0.5, v178
	v_fma_f32 v59, v59, 0.5, v179
	global_store_dwordx4 v148, v[56:59], s[88:89] offset:64
	v_cvt_pk_bf16_f32 v176, v56, v57
	v_cvt_pk_bf16_f32 v177, v58, v59
	global_store_dwordx2 v149, v[176:177], s[92:93] offset:32
	v_fmac_f32_e32 v159, v56, v56
	v_fmac_f32_e32 v159, v57, v57
	v_fmac_f32_e32 v159, v58, v58
	v_fmac_f32_e32 v159, v59, v59
	global_load_dwordx4 v[176:179], v148, s[86:87] offset:64
	s_waitcnt vmcnt(36)
	v_fma_f32 v52, v52, 0.5, v180
	v_fma_f32 v53, v53, 0.5, v181
	v_fma_f32 v54, v54, 0.5, v182
	v_fma_f32 v55, v55, 0.5, v183
	global_store_dwordx4 v148, v[52:55], s[88:89] offset:512
	v_cvt_pk_bf16_f32 v180, v52, v53
	v_cvt_pk_bf16_f32 v181, v54, v55
	global_store_dwordx2 v149, v[180:181], s[92:93] offset:256
	v_fmac_f32_e32 v159, v52, v52
	v_fmac_f32_e32 v159, v53, v53
	v_fmac_f32_e32 v159, v54, v54
	v_fmac_f32_e32 v159, v55, v55
	global_load_dwordx4 v[180:183], v148, s[86:87] offset:512
	s_waitcnt vmcnt(36)
	v_fma_f32 v48, v48, 0.5, v184
	v_fma_f32 v49, v49, 0.5, v185
	v_fma_f32 v50, v50, 0.5, v186
	v_fma_f32 v51, v51, 0.5, v187
	global_store_dwordx4 v148, v[48:51], s[88:89] offset:576
	v_cvt_pk_bf16_f32 v184, v48, v49
	v_cvt_pk_bf16_f32 v185, v50, v51
	global_store_dwordx2 v149, v[184:185], s[92:93] offset:288
	v_fmac_f32_e32 v159, v48, v48
	v_fmac_f32_e32 v159, v49, v49
	v_fmac_f32_e32 v159, v50, v50
	v_fmac_f32_e32 v159, v51, v51
	global_load_dwordx4 v[184:187], v148, s[86:87] offset:576
	s_nop 0
	ds_bpermute_b32 v215, v212, v159
	s_waitcnt lgkmcnt(0)
	v_add_f32_e32 v159, v159, v215
	s_nop 0
	ds_bpermute_b32 v215, v213, v159
	s_waitcnt lgkmcnt(0)
	v_add_f32_e32 v159, v159, v215
	v_cmp_eq_u32_e32 vcc, 0, v214
	s_and_saveexec_b64 s[98:99], vcc
	global_store_dword v158, v159, s[100:101]
	s_mov_b64 exec, s[98:99]
	s_add_u32 s88, s88, 0x10000
	s_addc_u32 s89, s89, 0
	s_add_u32 s92, s92, 0x8000
	s_addc_u32 s93, s93, 0
	s_add_u32 s100, s100, 0x400
	s_addc_u32 s101, s101, 0
	s_waitcnt vmcnt(36)
	v_fma_f32 v44, v44, 0.5, v188
	v_fma_f32 v45, v45, 0.5, v189
	v_fma_f32 v46, v46, 0.5, v190
	v_fma_f32 v47, v47, 0.5, v191
	global_store_dwordx4 v148, v[44:47], s[88:89]
	v_cvt_pk_bf16_f32 v188, v44, v45
	v_cvt_pk_bf16_f32 v189, v46, v47
	global_store_dwordx2 v149, v[188:189], s[92:93]
	v_mul_f32_e32 v159, v44, v44
	v_fmac_f32_e32 v159, v45, v45
	v_fmac_f32_e32 v159, v46, v46
	v_fmac_f32_e32 v159, v47, v47
	s_waitcnt vmcnt(35)
	v_fma_f32 v40, v40, 0.5, v192
	v_fma_f32 v41, v41, 0.5, v193
	v_fma_f32 v42, v42, 0.5, v194
	v_fma_f32 v43, v43, 0.5, v195
	global_store_dwordx4 v148, v[40:43], s[88:89] offset:64
	v_cvt_pk_bf16_f32 v192, v40, v41
	v_cvt_pk_bf16_f32 v193, v42, v43
	global_store_dwordx2 v149, v[192:193], s[92:93] offset:32
	v_fmac_f32_e32 v159, v40, v40
	v_fmac_f32_e32 v159, v41, v41
	v_fmac_f32_e32 v159, v42, v42
	v_fmac_f32_e32 v159, v43, v43
	s_waitcnt vmcnt(34)
	v_fma_f32 v36, v36, 0.5, v196
	v_fma_f32 v37, v37, 0.5, v197
	v_fma_f32 v38, v38, 0.5, v198
	v_fma_f32 v39, v39, 0.5, v199
	global_store_dwordx4 v148, v[36:39], s[88:89] offset:512
	v_cvt_pk_bf16_f32 v196, v36, v37
	v_cvt_pk_bf16_f32 v197, v38, v39
	global_store_dwordx2 v149, v[196:197], s[92:93] offset:256
	v_fmac_f32_e32 v159, v36, v36
	v_fmac_f32_e32 v159, v37, v37
	v_fmac_f32_e32 v159, v38, v38
	v_fmac_f32_e32 v159, v39, v39
	s_waitcnt vmcnt(33)
	v_fma_f32 v32, v32, 0.5, v200
	v_fma_f32 v33, v33, 0.5, v201
	v_fma_f32 v34, v34, 0.5, v202
	v_fma_f32 v35, v35, 0.5, v203
	global_store_dwordx4 v148, v[32:35], s[88:89] offset:576
	v_cvt_pk_bf16_f32 v200, v32, v33
	v_cvt_pk_bf16_f32 v201, v34, v35
	global_store_dwordx2 v149, v[200:201], s[92:93] offset:288
	v_fmac_f32_e32 v159, v32, v32
	v_fmac_f32_e32 v159, v33, v33
	v_fmac_f32_e32 v159, v34, v34
	v_fmac_f32_e32 v159, v35, v35
	s_nop 0
	ds_bpermute_b32 v215, v212, v159
	s_waitcnt lgkmcnt(0)
	v_add_f32_e32 v159, v159, v215
	s_nop 0
	ds_bpermute_b32 v215, v213, v159
	s_waitcnt lgkmcnt(0)
	v_add_f32_e32 v159, v159, v215
	v_cmp_eq_u32_e32 vcc, 0, v214
	s_and_saveexec_b64 s[98:99], vcc
	global_store_dword v158, v159, s[100:101]
	s_mov_b64 exec, s[98:99]
	s_add_u32 s88, s88, 0x10000
	s_addc_u32 s89, s89, 0
	s_add_u32 s92, s92, 0x8000
	s_addc_u32 s93, s93, 0
	s_add_u32 s100, s100, 0x400
	s_addc_u32 s101, s101, 0
	s_waitcnt vmcnt(32)
	v_fma_f32 v28, v28, 0.5, v144
	v_fma_f32 v29, v29, 0.5, v145
	v_fma_f32 v30, v30, 0.5, v146
	v_fma_f32 v31, v31, 0.5, v147
	global_store_dwordx4 v148, v[28:31], s[88:89]
	v_cvt_pk_bf16_f32 v144, v28, v29
	v_cvt_pk_bf16_f32 v145, v30, v31
	global_store_dwordx2 v149, v[144:145], s[92:93]
	v_mul_f32_e32 v159, v28, v28
	v_fmac_f32_e32 v159, v29, v29
	v_fmac_f32_e32 v159, v30, v30
	v_fmac_f32_e32 v159, v31, v31
	s_waitcnt vmcnt(31)
	v_fma_f32 v24, v24, 0.5, v160
	v_fma_f32 v25, v25, 0.5, v161
	v_fma_f32 v26, v26, 0.5, v162
	v_fma_f32 v27, v27, 0.5, v163
	global_store_dwordx4 v148, v[24:27], s[88:89] offset:64
	v_cvt_pk_bf16_f32 v160, v24, v25
	v_cvt_pk_bf16_f32 v161, v26, v27
	global_store_dwordx2 v149, v[160:161], s[92:93] offset:32
	v_fmac_f32_e32 v159, v24, v24
	v_fmac_f32_e32 v159, v25, v25
	v_fmac_f32_e32 v159, v26, v26
	v_fmac_f32_e32 v159, v27, v27
	s_waitcnt vmcnt(30)
	v_fma_f32 v20, v20, 0.5, v164
	v_fma_f32 v21, v21, 0.5, v165
	v_fma_f32 v22, v22, 0.5, v166
	v_fma_f32 v23, v23, 0.5, v167
	global_store_dwordx4 v148, v[20:23], s[88:89] offset:512
	v_cvt_pk_bf16_f32 v164, v20, v21
	v_cvt_pk_bf16_f32 v165, v22, v23
	global_store_dwordx2 v149, v[164:165], s[92:93] offset:256
	v_fmac_f32_e32 v159, v20, v20
	v_fmac_f32_e32 v159, v21, v21
	v_fmac_f32_e32 v159, v22, v22
	v_fmac_f32_e32 v159, v23, v23
	s_waitcnt vmcnt(29)
	v_fma_f32 v16, v16, 0.5, v168
	v_fma_f32 v17, v17, 0.5, v169
	v_fma_f32 v18, v18, 0.5, v170
	v_fma_f32 v19, v19, 0.5, v171
	global_store_dwordx4 v148, v[16:19], s[88:89] offset:576
	v_cvt_pk_bf16_f32 v168, v16, v17
	v_cvt_pk_bf16_f32 v169, v18, v19
	global_store_dwordx2 v149, v[168:169], s[92:93] offset:288
	v_fmac_f32_e32 v159, v16, v16
	v_fmac_f32_e32 v159, v17, v17
	v_fmac_f32_e32 v159, v18, v18
	v_fmac_f32_e32 v159, v19, v19
	s_nop 0
	ds_bpermute_b32 v215, v212, v159
	s_waitcnt lgkmcnt(0)
	v_add_f32_e32 v159, v159, v215
	s_nop 0
	ds_bpermute_b32 v215, v213, v159
	s_waitcnt lgkmcnt(0)
	v_add_f32_e32 v159, v159, v215
	v_cmp_eq_u32_e32 vcc, 0, v214
	s_and_saveexec_b64 s[98:99], vcc
	global_store_dword v158, v159, s[100:101]
	s_mov_b64 exec, s[98:99]
	s_add_u32 s88, s88, 0x10000
	s_addc_u32 s89, s89, 0
	s_add_u32 s92, s92, 0x8000
	s_addc_u32 s93, s93, 0
	s_add_u32 s100, s100, 0x400
	s_addc_u32 s101, s101, 0
	s_waitcnt vmcnt(28)
	v_fma_f32 v12, v12, 0.5, v172
	v_fma_f32 v13, v13, 0.5, v173
	v_fma_f32 v14, v14, 0.5, v174
	v_fma_f32 v15, v15, 0.5, v175
	global_store_dwordx4 v148, v[12:15], s[88:89]
	v_cvt_pk_bf16_f32 v172, v12, v13
	v_cvt_pk_bf16_f32 v173, v14, v15
	global_store_dwordx2 v149, v[172:173], s[92:93]
	v_mul_f32_e32 v159, v12, v12
	v_fmac_f32_e32 v159, v13, v13
	v_fmac_f32_e32 v159, v14, v14
	v_fmac_f32_e32 v159, v15, v15
	s_waitcnt vmcnt(27)
	v_fma_f32 v8, v8, 0.5, v176
	v_fma_f32 v9, v9, 0.5, v177
	v_fma_f32 v10, v10, 0.5, v178
	v_fma_f32 v11, v11, 0.5, v179
	global_store_dwordx4 v148, v[8:11], s[88:89] offset:64
	v_cvt_pk_bf16_f32 v176, v8, v9
	v_cvt_pk_bf16_f32 v177, v10, v11
	global_store_dwordx2 v149, v[176:177], s[92:93] offset:32
	v_fmac_f32_e32 v159, v8, v8
	v_fmac_f32_e32 v159, v9, v9
	v_fmac_f32_e32 v159, v10, v10
	v_fmac_f32_e32 v159, v11, v11
	s_waitcnt vmcnt(26)
	v_fma_f32 v4, v4, 0.5, v180
	v_fma_f32 v5, v5, 0.5, v181
	v_fma_f32 v6, v6, 0.5, v182
	v_fma_f32 v7, v7, 0.5, v183
	global_store_dwordx4 v148, v[4:7], s[88:89] offset:512
	v_cvt_pk_bf16_f32 v180, v4, v5
	v_cvt_pk_bf16_f32 v181, v6, v7
	global_store_dwordx2 v149, v[180:181], s[92:93] offset:256
	v_fmac_f32_e32 v159, v4, v4
	v_fmac_f32_e32 v159, v5, v5
	v_fmac_f32_e32 v159, v6, v6
	v_fmac_f32_e32 v159, v7, v7
	s_waitcnt vmcnt(25)
	v_fma_f32 v0, v0, 0.5, v184
	v_fma_f32 v1, v1, 0.5, v185
	v_fma_f32 v2, v2, 0.5, v186
	v_fma_f32 v3, v3, 0.5, v187
	global_store_dwordx4 v148, v[0:3], s[88:89] offset:576
	v_cvt_pk_bf16_f32 v184, v0, v1
	v_cvt_pk_bf16_f32 v185, v2, v3
	global_store_dwordx2 v149, v[184:185], s[92:93] offset:288
	v_fmac_f32_e32 v159, v0, v0
	v_fmac_f32_e32 v159, v1, v1
	v_fmac_f32_e32 v159, v2, v2
	v_fmac_f32_e32 v159, v3, v3
	s_nop 0
	ds_bpermute_b32 v215, v212, v159
	s_waitcnt lgkmcnt(0)
	v_add_f32_e32 v159, v159, v215
	s_nop 0
	ds_bpermute_b32 v215, v213, v159
	s_waitcnt lgkmcnt(0)
	v_add_f32_e32 v159, v159, v215
	v_cmp_eq_u32_e32 vcc, 0, v214
	s_and_saveexec_b64 s[98:99], vcc
	global_store_dword v158, v159, s[100:101]
	s_mov_b64 exec, s[98:99]
	s_and_b64 vcc, exec, s[10:11]
	s_mov_b64 s[10:11], -1
	s_cbranch_vccnz .LBB0_259
	s_andn2_b64 vcc, exec, s[26:27]
	s_cbranch_vccnz .LBB0_258
	s_barrier
	s_branch .LBB0_258

.LBB0_326:
.LBB0_347:
	s_waitcnt vmcnt(0) lgkmcnt(0)
	s_waitcnt lgkmcnt(0)
	s_barrier
	s_waitcnt vmcnt(0)
	s_barrier
	s_and_saveexec_b64 s[8:9], s[4:5]
	s_cbranch_execz .LBB0_399
	s_add_i32 s10, 0, 0x27ff0
	v_mov_b32_e32 v0, s10
	s_waitcnt vmcnt(0) expcnt(0) lgkmcnt(0)
	ds_read_b32 v2, v0
	s_add_i32 s10, 0, 0x27ff4
	v_mov_b32_e32 v0, s10
	ds_read_b32 v0, v0
	s_waitcnt lgkmcnt(1)
	v_cmp_ne_u32_e32 vcc, 0, v2
	s_cbranch_vccnz .LBB0_363
	s_add_u32 s10, s38, 0x4200
	s_addc_u32 s11, s39, 0
	s_add_u32 s12, s38, 0x4400
	s_addc_u32 s13, s39, 0
	s_add_u32 s16, s38, 0x4500
	s_addc_u32 s17, s39, 0
	s_add_u32 s18, s38, 0x4600
	s_addc_u32 s19, s39, 0
	s_add_u32 s24, s38, 0x4700
	s_addc_u32 s25, s39, 0
	s_add_u32 s26, s38, 0x4800
	s_addc_u32 s27, s39, 0
	s_add_u32 s28, s38, 0x4900
	s_addc_u32 s29, s39, 0
	s_add_u32 s30, s38, 0x4a00
	s_addc_u32 s31, s39, 0
	s_add_u32 s40, s38, 0x4b00
	s_addc_u32 s41, s39, 0
	s_add_u32 s42, s38, 0x4c00
	s_addc_u32 s43, s39, 0
	s_add_u32 s50, s38, 0x4d00
	s_addc_u32 s51, s39, 0
	s_add_u32 s52, s38, 0x4e00
	s_addc_u32 s53, s39, 0
	s_add_u32 s54, s38, 0x4f00
	s_addc_u32 s55, s39, 0
	s_add_u32 s56, s38, 0x5000
	s_addc_u32 s57, s39, 0
	s_add_u32 s58, s38, 0x5100
	s_addc_u32 s59, s39, 0
	s_add_u32 s60, s38, 0x5200
	s_addc_u32 s61, s39, 0
	s_mul_i32 s35, s47, s85
	s_add_u32 s62, s38, 0x5300
	s_mul_i32 s35, s35, s46
	s_addc_u32 s63, s39, 0
	s_mov_b32 s70, 1
	v_mov_b32_e32 v16, 0
	s_branch .LBB0_351

.LBB0_508:
	s_or_b64 exec, exec, s[10:11]
	s_waitcnt lgkmcnt(0)
	v_mov_b32_e32 v0, v206
	v_mov_b32_e32 v64, v206
	s_barrier
	s_mov_b64 s[98:99], s[8:9]
	s_cmp_gt_i32 s2, 0x7f
	s_cbranch_scc0 .Lmemkv_skip
	s_add_i32 s35, s2, 0xffffff80
	v_mov_b32_e32 v9, v206
	s_cmpk_gt_u32 s35, 0xff
	v_readfirstlane_b32 s8, v9
	s_cbranch_scc1 .Lmemkv_skip
	v_lshlrev_b32_e32 v0, 4, v9
	s_waitcnt lgkmcnt(0)
	v_add_u32_e32 v1, 0x2000, v0
	v_ashrrev_i32_e32 v2, 31, v1
	v_lshrrev_b32_e32 v2, 22, v2
	v_add_u32_e32 v2, v1, v2
	v_ashrrev_i32_e32 v8, 10, v2
	v_mul_i32_i24_e32 v3, 0x400, v8
	v_sub_u32_e32 v1, v1, v3
	v_lshrrev_b32_e32 v3, 4, v1
	v_bitop3_b32 v1, v3, v1, 32 bitop3:0x6c
	v_ashrrev_i32_e32 v3, 31, v1
	v_lshrrev_b32_e32 v3, 26, v3
	v_add_u32_e32 v3, v1, v3
	v_ashrrev_i32_e32 v10, 6, v3
	v_and_b32_e32 v3, 0xc0, v3
	v_sub_u32_e32 v1, v1, v3
	v_mov_b32_e32 v3, 1
	v_lshlrev_b32_e32 v2, 5, v8
	v_ashrrev_i16_sdwa v1, v3, sext(v1) dst_sel:DWORD dst_unused:UNUSED_PAD src0_sel:DWORD src1_sel:BYTE_0
	v_and_b32_e32 v2, 32, v2
	v_bfe_i32 v11, v1, 0, 16
	v_add_u32_e32 v1, v2, v11
	v_lshlrev_b32_e32 v2, 3, v8
	v_and_b32_e32 v2, 0x1ffff0, v2
	v_add_lshl_u32 v2, v10, v2, 11
	v_lshl_add_u32 v128, v1, 1, v2
	v_bfe_i32 v2, v9, 27, 1
	v_lshrrev_b32_e32 v2, 22, v2
	v_add_u32_e32 v2, v0, v2
	v_and_b32_e32 v2, 0xfffffc00, v2
	v_sub_u32_e32 v0, v0, v2
	v_lshrrev_b32_e32 v2, 4, v0
	v_bitop3_b32 v0, v2, v0, 32 bitop3:0x6c
	v_ashrrev_i32_e32 v2, 31, v0
	s_add_u32 s54, s38, 0x5e00000
	v_ashrrev_i32_e32 v1, 31, v9
	v_lshrrev_b32_e32 v2, 26, v2
	s_addc_u32 s55, s39, 0
	v_lshrrev_b32_e32 v1, 26, v1
	v_add_u32_e32 v2, v0, v2
	s_add_u32 s56, s38, 0x2700000
	v_add_u32_e32 v1, v9, v1
	v_ashrrev_i32_e32 v13, 6, v2
	v_and_b32_e32 v2, 0xc0, v2
	s_addc_u32 s57, s39, 0
	v_ashrrev_i32_e32 v12, 6, v1
	v_sub_u32_e32 v0, v0, v2
	s_lshl_b32 s10, s35, 2
	v_lshlrev_b32_e32 v1, 5, v12
	v_ashrrev_i16_sdwa v0, v3, sext(v0) dst_sel:DWORD dst_unused:UNUSED_PAD src0_sel:DWORD src1_sel:BYTE_0
	s_and_b32 s10, s10, 28
	s_bfe_u32 s11, s35, 0x20003
	s_ashr_i32 s24, s8, 6
	v_and_b32_e32 v1, 32, v1
	v_bfe_i32 v14, v0, 0, 16
	s_or_b32 s75, s10, s11
	s_bfe_u32 s18, s35, 0x60005
	s_ashr_i32 s9, s8, 8
	s_lshl_b32 s58, s24, 10
	v_add_u32_e32 v0, v1, v14
	v_lshlrev_b32_e32 v1, 3, v12
	s_lshl_b32 s12, s75, 19
	s_lshl_b32 s10, s18, 19
	v_and_b32_e32 v1, 0x1ffff0, v1
	s_add_u32 s50, s56, s10
	v_add_lshl_u32 v1, v13, v1, 11
	s_addc_u32 s51, s57, 0
	s_add_i32 s59, s58, 0
	v_lshl_add_u32 v130, v0, 1, v1
	s_add_i32 m0, s59, 0x10000
	v_mov_b32_e32 v133, 0
	global_load_lds_dwordx4 v130, s[50:51]
	s_add_i32 m0, s59, 0x12000
	s_add_u32 s10, s50, 0x40000
	global_load_lds_dwordx4 v128, s[50:51]
	s_addc_u32 s11, s51, 0
	s_add_i32 m0, s59, 0x14000
	v_mov_b32_e32 v131, v133
	global_load_lds_dwordx4 v130, s[10:11]
	s_add_i32 m0, s59, 0x16000
	v_mov_b32_e32 v129, v133
	global_load_lds_dwordx4 v128, s[10:11]
	s_add_u32 s10, s54, s12
	s_addc_u32 s11, s55, 0
	s_add_i32 s60, s59, 0x2000
	s_mov_b32 m0, s59
	s_add_u32 s12, s10, 0x40000
	global_load_lds_dwordx4 v130, s[10:11]
	s_mov_b32 m0, s60
	s_addc_u32 s13, s11, 0
	s_add_i32 s61, s59, 0x4000
	global_load_lds_dwordx4 v128, s[10:11]
	s_mov_b32 m0, s61
	s_add_i32 s62, s59, 0x6000
	global_load_lds_dwordx4 v130, s[12:13]
	s_mov_b32 m0, s62
	s_cmp_eq_u32 s9, 1
	global_load_lds_dwordx4 v128, s[12:13]
	s_load_dwordx2 s[12:13], s[0:1], 0x110
	s_mov_b32 s63, 0
	v_lshl_add_u64 v[6:7], s[50:51], 0, v[130:131]
	v_lshl_add_u64 v[4:5], s[50:51], 0, v[128:129]
	v_lshl_add_u64 v[0:1], s[10:11], 0, v[130:131]
	s_cselect_b64 s[16:17], -1, 0
	s_cmp_lg_u32 s9, 1
	v_lshl_add_u64 v[2:3], s[10:11], 0, v[128:129]
	s_cbranch_scc1 .LBB0_330
	s_barrier
.LBB0_330:
	s_and_b32 s73, 0xffff, s18
	s_add_i32 s64, s46, 0xffffff80
	s_add_u32 s18, s38, 0x5a00000
	s_addc_u32 s19, s39, 0
	s_lshl_b32 s24, s24, 5
	s_and_b32 s29, s24, 0x60
	s_mov_b64 s[24:25], 0x80
	s_add_i32 m0, s59, 0x18000
	v_lshl_add_u64 v[6:7], v[6:7], 0, s[24:25]
	s_lshl_b32 s28, s9, 13
	s_lshl_b32 s30, s29, 7
	s_waitcnt vmcnt(2)
	s_barrier
	global_load_lds_dwordx4 v[6:7], off
	v_lshl_add_u64 v[4:5], v[4:5], 0, s[24:25]
	s_add_i32 m0, s59, 0x1a000
	s_add_i32 s65, s59, 0x8000
	s_add_i32 s66, s59, 0xa000
	global_load_lds_dwordx4 v[4:5], off
	v_lshl_add_u64 v[0:1], v[0:1], 0, s[24:25]
	s_mov_b32 m0, s65
	s_add_u32 s26, s50, 0x40080
	global_load_lds_dwordx4 v[0:1], off
	v_lshl_add_u64 v[0:1], v[2:3], 0, s[24:25]
	s_mov_b32 m0, s66
	s_addc_u32 s27, s51, 0
	global_load_lds_dwordx4 v[0:1], off
	s_add_i32 m0, s59, 0x1c000
	v_lshl_add_u64 v[0:1], s[26:27], 0, v[130:131]
	global_load_lds_dwordx4 v[0:1], off
	v_lshl_add_u64 v[0:1], s[26:27], 0, v[128:129]
	s_add_i32 m0, s59, 0x1e000
	s_cmpk_lt_u32 s8, 0x100
	global_load_lds_dwordx4 v[0:1], off
	v_bfe_u32 v1, v9, 4, 2
	v_and_b32_e32 v0, 15, v9
	v_lshlrev_b32_e32 v2, 4, v1
	v_lshl_or_b32 v148, s9, 6, v0
	v_lshl_or_b32 v0, v0, 6, v2
	v_lshlrev_b32_e32 v2, 2, v9
	v_and_b32_e32 v2, 32, v2
	v_bitop3_b32 v3, v0, s28, v2 bitop3:0xde
	v_bitop3_b32 v149, v0, s30, v2 bitop3:0xde
	v_lshlrev_b32_e32 v0, 14, v12
	v_and_b32_e32 v0, 0xffff8000, v0
	v_lshl_or_b32 v150, v1, 2, s29
	v_lshl_add_u32 v0, v13, 11, v0
	v_and_b32_e32 v1, 1, v12
	v_lshl_or_b32 v0, v1, 6, v0
	v_lshl_add_u32 v134, v14, 1, v0
	v_lshlrev_b32_e32 v0, 14, v8
	v_and_b32_e32 v0, 0xffff8000, v0
	s_waitcnt vmcnt(6)
	v_lshl_add_u32 v0, v10, 11, v0
	v_and_b32_e32 v1, 1, v8
	s_cselect_b64 s[26:27], -1, 0
	v_lshl_or_b32 v0, v1, 6, v0
	s_add_i32 s68, 0, 0x10000
	s_add_i32 s69, 0, 0x14000
	s_ashr_i32 s67, s64, 31
	v_mov_b32_e32 v135, v133
	v_lshl_add_u32 v136, v11, 1, v0
	v_mov_b32_e32 v137, v133
	v_mov_b64_e32 v[138:139], 0x100
	v_mov_b64_e32 v[140:141], 0xff
	v_add_u32_e32 v151, s68, v149
	v_add_u32_e32 v152, s69, v149
	v_add_u32_e32 v153, 0, v3
	s_mov_b32 s70, 0x16990000
	s_mov_b32 s71, 0x8600000
	v_mov_b32_e32 v154, 0x358637bd
	s_mov_b32 s72, 0x800000
	s_barrier
	s_branch .LBB0_333

.Lmemkv_skip:
	s_mov_b64 s[8:9], s[98:99]
	v_mov_b32_e32 v0, v206
	v_mov_b32_e32 v64, v206
	s_nop 1
	s_load_dwordx4 s[40:43], s[0:1], 0x78
	s_load_dwordx2 s[52:53], s[0:1], 0x98
	s_add_u32 s50, s38, 0x11f00000
	s_addc_u32 s51, s39, 0
	s_and_b32 s76, s2, 3
	v_readfirstlane_b32 s10, v64
	s_lshl_b32 s75, s76, 7
	s_ashr_i32 s35, s10, 6
	s_cmpk_gt_i32 s2, 0x7f
	v_and_b32_e32 v66, 63, v64
	s_cbranch_scc0 .LBB0_517
	s_add_i32 s77, s2, 0xffffff80
	s_lshl_b32 s10, s77, 3
	s_add_i32 s26, s34, 0xfffffc00
	s_add_i32 s10, s35, s10
	s_cmpk_gt_i32 s10, 0x40ff
	s_cbranch_scc1 .LBB0_518
	s_add_i32 s11, s35, s33
	v_lshlrev_b32_e32 v4, 3, v66
	v_mov_b32_e32 v1, 0
	v_lshlrev_b32_e32 v0, 4, v66
	s_add_i32 s12, s11, 0xffffbc00
	s_ashr_i32 s11, s10, 31
	v_lshl_add_u64 v[0:1], s[50:51], 0, v[0:1]
	s_ashr_i32 s27, s26, 31
	s_mov_b32 s13, 0
	v_mov_b32_e32 v2, 0x2c00
	v_lshlrev_b32_e32 v3, 2, v4
	s_mov_b64 s[14:15], s[10:11]
	s_branch .LBB0_513

.LBB0_1010:
	v_lshrrev_b32_e32 v136, 6, v206
	v_and_b32_e32 v147, 63, v206
	v_lshrrev_b32_e32 v146, 2, v136
	v_and_b32_e32 v136, 3, v136
	v_lshlrev_b32_e32 v146, 6, v146
	v_lshrrev_b32_e32 v218, 4, v147
	v_and_b32_e32 v219, 15, v147
	v_xor_b32_e32 v216, 16, v147
	v_xor_b32_e32 v217, 32, v147
	v_lshlrev_b32_e32 v216, 2, v216
	v_lshlrev_b32_e32 v217, 2, v217
	v_add_u32_e32 v146, v146, v219
	v_lshlrev_b32_e32 v147, 5, v136
	v_lshl_add_u32 v147, v218, 2, v147
	s_lshl_b32 vcc_lo, s24, 8
	v_add_u32_e32 v146, vcc_lo, v146
	s_lshl_b32 vcc_lo, s20, 8
	v_add_u32_e32 v147, vcc_lo, v147
	v_lshlrev_b32_e32 v152, 12, v146
	v_lshl_add_u32 v152, v147, 2, v152
	v_lshlrev_b32_e32 v153, 11, v146
	v_lshl_add_u32 v153, v147, 1, v153
	s_lshl_b32 vcc_lo, s20, 2
	v_add_u32_e32 v136, vcc_lo, v136
	v_lshlrev_b32_e32 v210, 6, v146
	v_lshl_add_u32 v210, v136, 2, v210
	s_mov_b32 s86, s94
	s_mov_b32 s87, s95
	s_mov_b32 s88, s94
	s_mov_b32 s89, s95
	s_add_u32 s92, s96, 0x9e00000
	s_addc_u32 s93, s97, 0
	s_add_u32 s100, s96, 0x4b00000
	s_addc_u32 s101, s97, 0
	global_load_dwordx4 v[148:151], v152, s[86:87]
	global_load_dwordx4 v[160:163], v152, s[86:87] offset:64
	global_load_dwordx4 v[164:167], v152, s[86:87] offset:512
	global_load_dwordx4 v[168:171], v152, s[86:87] offset:576
	s_add_u32 s86, s86, 0x10000
	s_addc_u32 s87, s87, 0
	global_load_dwordx4 v[172:175], v152, s[86:87]
	global_load_dwordx4 v[176:179], v152, s[86:87] offset:64
	global_load_dwordx4 v[180:183], v152, s[86:87] offset:512
	global_load_dwordx4 v[184:187], v152, s[86:87] offset:576
	s_add_u32 s86, s86, 0x10000
	s_addc_u32 s87, s87, 0
	global_load_dwordx4 v[188:191], v152, s[86:87]
	global_load_dwordx4 v[192:195], v152, s[86:87] offset:64
	global_load_dwordx4 v[196:199], v152, s[86:87] offset:512
	global_load_dwordx4 v[200:203], v152, s[86:87] offset:576
	s_add_u32 s86, s86, 0x10000
	s_addc_u32 s87, s87, 0
	global_load_dwordx4 v[212:215], v152, s[86:87]
	s_waitcnt vmcnt(12)
	v_add_f32_e32 v124, v124, v148
	v_add_f32_e32 v125, v125, v149
	v_add_f32_e32 v126, v126, v150
	v_add_f32_e32 v127, v127, v151
	global_store_dwordx4 v152, v[124:127], s[88:89]
	v_cvt_pk_bf16_f32 v148, v124, v125
	v_cvt_pk_bf16_f32 v149, v126, v127
	global_store_dwordx2 v153, v[148:149], s[92:93]
	v_mul_f32_e32 v211, v124, v124
	v_fmac_f32_e32 v211, v125, v125
	v_fmac_f32_e32 v211, v126, v126
	v_fmac_f32_e32 v211, v127, v127
	global_load_dwordx4 v[148:151], v152, s[86:87] offset:64
	s_waitcnt vmcnt(14)
	v_add_f32_e32 v120, v120, v160
	v_add_f32_e32 v121, v121, v161
	v_add_f32_e32 v122, v122, v162
	v_add_f32_e32 v123, v123, v163
	global_store_dwordx4 v152, v[120:123], s[88:89] offset:64
	v_cvt_pk_bf16_f32 v160, v120, v121
	v_cvt_pk_bf16_f32 v161, v122, v123
	global_store_dwordx2 v153, v[160:161], s[92:93] offset:32
	v_fmac_f32_e32 v211, v120, v120
	v_fmac_f32_e32 v211, v121, v121
	v_fmac_f32_e32 v211, v122, v122
	v_fmac_f32_e32 v211, v123, v123
	global_load_dwordx4 v[160:163], v152, s[86:87] offset:512
	s_waitcnt vmcnt(16)
	v_add_f32_e32 v116, v116, v164
	v_add_f32_e32 v117, v117, v165
	v_add_f32_e32 v118, v118, v166
	v_add_f32_e32 v119, v119, v167
	global_store_dwordx4 v152, v[116:119], s[88:89] offset:512
	v_cvt_pk_bf16_f32 v164, v116, v117
	v_cvt_pk_bf16_f32 v165, v118, v119
	global_store_dwordx2 v153, v[164:165], s[92:93] offset:256
	v_fmac_f32_e32 v211, v116, v116
	v_fmac_f32_e32 v211, v117, v117
	v_fmac_f32_e32 v211, v118, v118
	v_fmac_f32_e32 v211, v119, v119
	global_load_dwordx4 v[164:167], v152, s[86:87] offset:576
	s_waitcnt vmcnt(18)
	v_add_f32_e32 v112, v112, v168
	v_add_f32_e32 v113, v113, v169
	v_add_f32_e32 v114, v114, v170
	v_add_f32_e32 v115, v115, v171
	global_store_dwordx4 v152, v[112:115], s[88:89] offset:576
	v_cvt_pk_bf16_f32 v168, v112, v113
	v_cvt_pk_bf16_f32 v169, v114, v115
	global_store_dwordx2 v153, v[168:169], s[92:93] offset:288
	v_fmac_f32_e32 v211, v112, v112
	v_fmac_f32_e32 v211, v113, v113
	v_fmac_f32_e32 v211, v114, v114
	v_fmac_f32_e32 v211, v115, v115
	s_add_u32 s86, s86, 0x50000
	s_addc_u32 s87, s87, 0
	global_load_dwordx4 v[168:171], v152, s[86:87]
	s_nop 0
	ds_bpermute_b32 v219, v216, v211
	s_waitcnt lgkmcnt(0)
	v_add_f32_e32 v211, v211, v219
	s_nop 0
	ds_bpermute_b32 v219, v217, v211
	s_waitcnt lgkmcnt(0)
	v_add_f32_e32 v211, v211, v219
	v_cmp_eq_u32_e32 vcc, 0, v218
	s_and_saveexec_b64 s[98:99], vcc
	global_store_dword v210, v211, s[100:101]
	s_mov_b64 exec, s[98:99]
	s_add_u32 s88, s88, 0x10000
	s_addc_u32 s89, s89, 0
	s_add_u32 s92, s92, 0x8000
	s_addc_u32 s93, s93, 0
	s_add_u32 s100, s100, 0x400
	s_addc_u32 s101, s101, 0
	s_waitcnt vmcnt(21)
	v_add_f32_e32 v108, v108, v172
	v_add_f32_e32 v109, v109, v173
	v_add_f32_e32 v110, v110, v174
	v_add_f32_e32 v111, v111, v175
	global_store_dwordx4 v152, v[108:111], s[88:89]
	v_cvt_pk_bf16_f32 v172, v108, v109
	v_cvt_pk_bf16_f32 v173, v110, v111
	global_store_dwordx2 v153, v[172:173], s[92:93]
	v_mul_f32_e32 v211, v108, v108
	v_fmac_f32_e32 v211, v109, v109
	v_fmac_f32_e32 v211, v110, v110
	v_fmac_f32_e32 v211, v111, v111
	global_load_dwordx4 v[172:175], v152, s[86:87] offset:64
	s_waitcnt vmcnt(23)
	v_add_f32_e32 v104, v104, v176
	v_add_f32_e32 v105, v105, v177
	v_add_f32_e32 v106, v106, v178
	v_add_f32_e32 v107, v107, v179
	global_store_dwordx4 v152, v[104:107], s[88:89] offset:64
	v_cvt_pk_bf16_f32 v176, v104, v105
	v_cvt_pk_bf16_f32 v177, v106, v107
	global_store_dwordx2 v153, v[176:177], s[92:93] offset:32
	v_fmac_f32_e32 v211, v104, v104
	v_fmac_f32_e32 v211, v105, v105
	v_fmac_f32_e32 v211, v106, v106
	v_fmac_f32_e32 v211, v107, v107
	global_load_dwordx4 v[176:179], v152, s[86:87] offset:512
	s_waitcnt vmcnt(25)
	v_add_f32_e32 v100, v100, v180
	v_add_f32_e32 v101, v101, v181
	v_add_f32_e32 v102, v102, v182
	v_add_f32_e32 v103, v103, v183
	global_store_dwordx4 v152, v[100:103], s[88:89] offset:512
	v_cvt_pk_bf16_f32 v180, v100, v101
	v_cvt_pk_bf16_f32 v181, v102, v103
	global_store_dwordx2 v153, v[180:181], s[92:93] offset:256
	v_fmac_f32_e32 v211, v100, v100
	v_fmac_f32_e32 v211, v101, v101
	v_fmac_f32_e32 v211, v102, v102
	v_fmac_f32_e32 v211, v103, v103
	global_load_dwordx4 v[180:183], v152, s[86:87] offset:576
	s_waitcnt vmcnt(27)
	v_add_f32_e32 v96, v96, v184
	v_add_f32_e32 v97, v97, v185
	v_add_f32_e32 v98, v98, v186
	v_add_f32_e32 v99, v99, v187
	global_store_dwordx4 v152, v[96:99], s[88:89] offset:576
	v_cvt_pk_bf16_f32 v184, v96, v97
	v_cvt_pk_bf16_f32 v185, v98, v99
	global_store_dwordx2 v153, v[184:185], s[92:93] offset:288
	v_fmac_f32_e32 v211, v96, v96
	v_fmac_f32_e32 v211, v97, v97
	v_fmac_f32_e32 v211, v98, v98
	v_fmac_f32_e32 v211, v99, v99
	s_add_u32 s86, s86, 0x10000
	s_addc_u32 s87, s87, 0
	global_load_dwordx4 v[184:187], v152, s[86:87]
	s_nop 0
	ds_bpermute_b32 v219, v216, v211
	s_waitcnt lgkmcnt(0)
	v_add_f32_e32 v211, v211, v219
	s_nop 0
	ds_bpermute_b32 v219, v217, v211
	s_waitcnt lgkmcnt(0)
	v_add_f32_e32 v211, v211, v219
	v_cmp_eq_u32_e32 vcc, 0, v218
	s_and_saveexec_b64 s[98:99], vcc
	global_store_dword v210, v211, s[100:101]
	s_mov_b64 exec, s[98:99]
	s_add_u32 s88, s88, 0x10000
	s_addc_u32 s89, s89, 0
	s_add_u32 s92, s92, 0x8000
	s_addc_u32 s93, s93, 0
	s_add_u32 s100, s100, 0x400
	s_addc_u32 s101, s101, 0
	s_waitcnt vmcnt(30)
	v_add_f32_e32 v92, v92, v188
	v_add_f32_e32 v93, v93, v189
	v_add_f32_e32 v94, v94, v190
	v_add_f32_e32 v95, v95, v191
	global_store_dwordx4 v152, v[92:95], s[88:89]
	v_cvt_pk_bf16_f32 v188, v92, v93
	v_cvt_pk_bf16_f32 v189, v94, v95
	global_store_dwordx2 v153, v[188:189], s[92:93]
	v_mul_f32_e32 v211, v92, v92
	v_fmac_f32_e32 v211, v93, v93
	v_fmac_f32_e32 v211, v94, v94
	v_fmac_f32_e32 v211, v95, v95
	global_load_dwordx4 v[188:191], v152, s[86:87] offset:64
	s_waitcnt vmcnt(32)
	v_add_f32_e32 v88, v88, v192
	v_add_f32_e32 v89, v89, v193
	v_add_f32_e32 v90, v90, v194
	v_add_f32_e32 v91, v91, v195
	global_store_dwordx4 v152, v[88:91], s[88:89] offset:64
	v_cvt_pk_bf16_f32 v192, v88, v89
	v_cvt_pk_bf16_f32 v193, v90, v91
	global_store_dwordx2 v153, v[192:193], s[92:93] offset:32
	v_fmac_f32_e32 v211, v88, v88
	v_fmac_f32_e32 v211, v89, v89
	v_fmac_f32_e32 v211, v90, v90
	v_fmac_f32_e32 v211, v91, v91
	global_load_dwordx4 v[192:195], v152, s[86:87] offset:512
	s_waitcnt vmcnt(34)
	v_add_f32_e32 v84, v84, v196
	v_add_f32_e32 v85, v85, v197
	v_add_f32_e32 v86, v86, v198
	v_add_f32_e32 v87, v87, v199
	global_store_dwordx4 v152, v[84:87], s[88:89] offset:512
	v_cvt_pk_bf16_f32 v196, v84, v85
	v_cvt_pk_bf16_f32 v197, v86, v87
	global_store_dwordx2 v153, v[196:197], s[92:93] offset:256
	v_fmac_f32_e32 v211, v84, v84
	v_fmac_f32_e32 v211, v85, v85
	v_fmac_f32_e32 v211, v86, v86
	v_fmac_f32_e32 v211, v87, v87
	global_load_dwordx4 v[196:199], v152, s[86:87] offset:576
	s_waitcnt vmcnt(36)
	v_add_f32_e32 v80, v80, v200
	v_add_f32_e32 v81, v81, v201
	v_add_f32_e32 v82, v82, v202
	v_add_f32_e32 v83, v83, v203
	global_store_dwordx4 v152, v[80:83], s[88:89] offset:576
	v_cvt_pk_bf16_f32 v200, v80, v81
	v_cvt_pk_bf16_f32 v201, v82, v83
	global_store_dwordx2 v153, v[200:201], s[92:93] offset:288
	v_fmac_f32_e32 v211, v80, v80
	v_fmac_f32_e32 v211, v81, v81
	v_fmac_f32_e32 v211, v82, v82
	v_fmac_f32_e32 v211, v83, v83
	s_add_u32 s86, s86, 0x10000
	s_addc_u32 s87, s87, 0
	global_load_dwordx4 v[200:203], v152, s[86:87]
	s_nop 0
	ds_bpermute_b32 v219, v216, v211
	s_waitcnt lgkmcnt(0)
	v_add_f32_e32 v211, v211, v219
	s_nop 0
	ds_bpermute_b32 v219, v217, v211
	s_waitcnt lgkmcnt(0)
	v_add_f32_e32 v211, v211, v219
	v_cmp_eq_u32_e32 vcc, 0, v218
	s_and_saveexec_b64 s[98:99], vcc
	global_store_dword v210, v211, s[100:101]
	s_mov_b64 exec, s[98:99]
	s_add_u32 s88, s88, 0x10000
	s_addc_u32 s89, s89, 0
	s_add_u32 s92, s92, 0x8000
	s_addc_u32 s93, s93, 0
	s_add_u32 s100, s100, 0x400
	s_addc_u32 s101, s101, 0
	s_waitcnt vmcnt(39)
	v_add_f32_e32 v76, v76, v212
	v_add_f32_e32 v77, v77, v213
	v_add_f32_e32 v78, v78, v214
	v_add_f32_e32 v79, v79, v215
	global_store_dwordx4 v152, v[76:79], s[88:89]
	v_cvt_pk_bf16_f32 v212, v76, v77
	v_cvt_pk_bf16_f32 v213, v78, v79
	global_store_dwordx2 v153, v[212:213], s[92:93]
	v_mul_f32_e32 v211, v76, v76
	v_fmac_f32_e32 v211, v77, v77
	v_fmac_f32_e32 v211, v78, v78
	v_fmac_f32_e32 v211, v79, v79
	global_load_dwordx4 v[212:215], v152, s[86:87] offset:64
	s_waitcnt vmcnt(39)
	v_add_f32_e32 v72, v72, v148
	v_add_f32_e32 v73, v73, v149
	v_add_f32_e32 v74, v74, v150
	v_add_f32_e32 v75, v75, v151
	global_store_dwordx4 v152, v[72:75], s[88:89] offset:64
	v_cvt_pk_bf16_f32 v148, v72, v73
	v_cvt_pk_bf16_f32 v149, v74, v75
	global_store_dwordx2 v153, v[148:149], s[92:93] offset:32
	v_fmac_f32_e32 v211, v72, v72
	v_fmac_f32_e32 v211, v73, v73
	v_fmac_f32_e32 v211, v74, v74
	v_fmac_f32_e32 v211, v75, v75
	global_load_dwordx4 v[148:151], v152, s[86:87] offset:512
	s_waitcnt vmcnt(39)
	v_add_f32_e32 v68, v68, v160
	v_add_f32_e32 v69, v69, v161
	v_add_f32_e32 v70, v70, v162
	v_add_f32_e32 v71, v71, v163
	global_store_dwordx4 v152, v[68:71], s[88:89] offset:512
	v_cvt_pk_bf16_f32 v160, v68, v69
	v_cvt_pk_bf16_f32 v161, v70, v71
	global_store_dwordx2 v153, v[160:161], s[92:93] offset:256
	v_fmac_f32_e32 v211, v68, v68
	v_fmac_f32_e32 v211, v69, v69
	v_fmac_f32_e32 v211, v70, v70
	v_fmac_f32_e32 v211, v71, v71
	global_load_dwordx4 v[160:163], v152, s[86:87] offset:576
	s_waitcnt vmcnt(39)
	v_add_f32_e32 v64, v64, v164
	v_add_f32_e32 v65, v65, v165
	v_add_f32_e32 v66, v66, v166
	v_add_f32_e32 v67, v67, v167
	global_store_dwordx4 v152, v[64:67], s[88:89] offset:576
	v_cvt_pk_bf16_f32 v164, v64, v65
	v_cvt_pk_bf16_f32 v165, v66, v67
	global_store_dwordx2 v153, v[164:165], s[92:93] offset:288
	v_fmac_f32_e32 v211, v64, v64
	v_fmac_f32_e32 v211, v65, v65
	v_fmac_f32_e32 v211, v66, v66
	v_fmac_f32_e32 v211, v67, v67
	s_add_u32 s86, s86, 0x10000
	s_addc_u32 s87, s87, 0
	global_load_dwordx4 v[164:167], v152, s[86:87]
	s_nop 0
	ds_bpermute_b32 v219, v216, v211
	s_waitcnt lgkmcnt(0)
	v_add_f32_e32 v211, v211, v219
	s_nop 0
	ds_bpermute_b32 v219, v217, v211
	s_waitcnt lgkmcnt(0)
	v_add_f32_e32 v211, v211, v219
	v_cmp_eq_u32_e32 vcc, 0, v218
	s_and_saveexec_b64 s[98:99], vcc
	global_store_dword v210, v211, s[100:101]
	s_mov_b64 exec, s[98:99]
	s_add_u32 s88, s88, 0x50000
	s_addc_u32 s89, s89, 0
	s_add_u32 s92, s92, 0x28000
	s_addc_u32 s93, s93, 0
	s_add_u32 s100, s100, 0x1400
	s_addc_u32 s101, s101, 0
	s_waitcnt vmcnt(40)
	v_add_f32_e32 v60, v60, v168
	v_add_f32_e32 v61, v61, v169
	v_add_f32_e32 v62, v62, v170
	v_add_f32_e32 v63, v63, v171
	global_store_dwordx4 v152, v[60:63], s[88:89]
	v_cvt_pk_bf16_f32 v168, v60, v61
	v_cvt_pk_bf16_f32 v169, v62, v63
	global_store_dwordx2 v153, v[168:169], s[92:93]
	v_mul_f32_e32 v211, v60, v60
	v_fmac_f32_e32 v211, v61, v61
	v_fmac_f32_e32 v211, v62, v62
	v_fmac_f32_e32 v211, v63, v63
	global_load_dwordx4 v[168:171], v152, s[86:87] offset:64
	s_waitcnt vmcnt(39)
	v_add_f32_e32 v56, v56, v172
	v_add_f32_e32 v57, v57, v173
	v_add_f32_e32 v58, v58, v174
	v_add_f32_e32 v59, v59, v175
	global_store_dwordx4 v152, v[56:59], s[88:89] offset:64
	v_cvt_pk_bf16_f32 v172, v56, v57
	v_cvt_pk_bf16_f32 v173, v58, v59
	global_store_dwordx2 v153, v[172:173], s[92:93] offset:32
	v_fmac_f32_e32 v211, v56, v56
	v_fmac_f32_e32 v211, v57, v57
	v_fmac_f32_e32 v211, v58, v58
	v_fmac_f32_e32 v211, v59, v59
	global_load_dwordx4 v[172:175], v152, s[86:87] offset:512
	s_waitcnt vmcnt(39)
	v_add_f32_e32 v52, v52, v176
	v_add_f32_e32 v53, v53, v177
	v_add_f32_e32 v54, v54, v178
	v_add_f32_e32 v55, v55, v179
	global_store_dwordx4 v152, v[52:55], s[88:89] offset:512
	v_cvt_pk_bf16_f32 v176, v52, v53
	v_cvt_pk_bf16_f32 v177, v54, v55
	global_store_dwordx2 v153, v[176:177], s[92:93] offset:256
	v_fmac_f32_e32 v211, v52, v52
	v_fmac_f32_e32 v211, v53, v53
	v_fmac_f32_e32 v211, v54, v54
	v_fmac_f32_e32 v211, v55, v55
	global_load_dwordx4 v[176:179], v152, s[86:87] offset:576
	s_waitcnt vmcnt(39)
	v_add_f32_e32 v48, v48, v180
	v_add_f32_e32 v49, v49, v181
	v_add_f32_e32 v50, v50, v182
	v_add_f32_e32 v51, v51, v183
	global_store_dwordx4 v152, v[48:51], s[88:89] offset:576
	v_cvt_pk_bf16_f32 v180, v48, v49
	v_cvt_pk_bf16_f32 v181, v50, v51
	global_store_dwordx2 v153, v[180:181], s[92:93] offset:288
	v_fmac_f32_e32 v211, v48, v48
	v_fmac_f32_e32 v211, v49, v49
	v_fmac_f32_e32 v211, v50, v50
	v_fmac_f32_e32 v211, v51, v51
	s_nop 0
	ds_bpermute_b32 v219, v216, v211
	s_waitcnt lgkmcnt(0)
	v_add_f32_e32 v211, v211, v219
	s_nop 0
	ds_bpermute_b32 v219, v217, v211
	s_waitcnt lgkmcnt(0)
	v_add_f32_e32 v211, v211, v219
	v_cmp_eq_u32_e32 vcc, 0, v218
	s_and_saveexec_b64 s[98:99], vcc
	global_store_dword v210, v211, s[100:101]
	s_mov_b64 exec, s[98:99]
	s_add_u32 s88, s88, 0x10000
	s_addc_u32 s89, s89, 0
	s_add_u32 s92, s92, 0x8000
	s_addc_u32 s93, s93, 0
	s_add_u32 s100, s100, 0x400
	s_addc_u32 s101, s101, 0
	s_waitcnt vmcnt(39)
	v_add_f32_e32 v44, v44, v184
	v_add_f32_e32 v45, v45, v185
	v_add_f32_e32 v46, v46, v186
	v_add_f32_e32 v47, v47, v187
	global_store_dwordx4 v152, v[44:47], s[88:89]
	v_cvt_pk_bf16_f32 v184, v44, v45
	v_cvt_pk_bf16_f32 v185, v46, v47
	global_store_dwordx2 v153, v[184:185], s[92:93]
	v_mul_f32_e32 v211, v44, v44
	v_fmac_f32_e32 v211, v45, v45
	v_fmac_f32_e32 v211, v46, v46
	v_fmac_f32_e32 v211, v47, v47
	s_waitcnt vmcnt(37)
	v_add_f32_e32 v40, v40, v188
	v_add_f32_e32 v41, v41, v189
	v_add_f32_e32 v42, v42, v190
	v_add_f32_e32 v43, v43, v191
	global_store_dwordx4 v152, v[40:43], s[88:89] offset:64
	v_cvt_pk_bf16_f32 v188, v40, v41
	v_cvt_pk_bf16_f32 v189, v42, v43
	global_store_dwordx2 v153, v[188:189], s[92:93] offset:32
	v_fmac_f32_e32 v211, v40, v40
	v_fmac_f32_e32 v211, v41, v41
	v_fmac_f32_e32 v211, v42, v42
	v_fmac_f32_e32 v211, v43, v43
	s_waitcnt vmcnt(36)
	v_add_f32_e32 v36, v36, v192
	v_add_f32_e32 v37, v37, v193
	v_add_f32_e32 v38, v38, v194
	v_add_f32_e32 v39, v39, v195
	global_store_dwordx4 v152, v[36:39], s[88:89] offset:512
	v_cvt_pk_bf16_f32 v192, v36, v37
	v_cvt_pk_bf16_f32 v193, v38, v39
	global_store_dwordx2 v153, v[192:193], s[92:93] offset:256
	v_fmac_f32_e32 v211, v36, v36
	v_fmac_f32_e32 v211, v37, v37
	v_fmac_f32_e32 v211, v38, v38
	v_fmac_f32_e32 v211, v39, v39
	s_waitcnt vmcnt(35)
	v_add_f32_e32 v32, v32, v196
	v_add_f32_e32 v33, v33, v197
	v_add_f32_e32 v34, v34, v198
	v_add_f32_e32 v35, v35, v199
	global_store_dwordx4 v152, v[32:35], s[88:89] offset:576
	v_cvt_pk_bf16_f32 v196, v32, v33
	v_cvt_pk_bf16_f32 v197, v34, v35
	global_store_dwordx2 v153, v[196:197], s[92:93] offset:288
	v_fmac_f32_e32 v211, v32, v32
	v_fmac_f32_e32 v211, v33, v33
	v_fmac_f32_e32 v211, v34, v34
	v_fmac_f32_e32 v211, v35, v35
	s_nop 0
	ds_bpermute_b32 v219, v216, v211
	s_waitcnt lgkmcnt(0)
	v_add_f32_e32 v211, v211, v219
	s_nop 0
	ds_bpermute_b32 v219, v217, v211
	s_waitcnt lgkmcnt(0)
	v_add_f32_e32 v211, v211, v219
	v_cmp_eq_u32_e32 vcc, 0, v218
	s_and_saveexec_b64 s[98:99], vcc
	global_store_dword v210, v211, s[100:101]
	s_mov_b64 exec, s[98:99]
	s_add_u32 s88, s88, 0x10000
	s_addc_u32 s89, s89, 0
	s_add_u32 s92, s92, 0x8000
	s_addc_u32 s93, s93, 0
	s_add_u32 s100, s100, 0x400
	s_addc_u32 s101, s101, 0
	s_waitcnt vmcnt(35)
	v_add_f32_e32 v28, v28, v200
	v_add_f32_e32 v29, v29, v201
	v_add_f32_e32 v30, v30, v202
	v_add_f32_e32 v31, v31, v203
	global_store_dwordx4 v152, v[28:31], s[88:89]
	v_cvt_pk_bf16_f32 v200, v28, v29
	v_cvt_pk_bf16_f32 v201, v30, v31
	global_store_dwordx2 v153, v[200:201], s[92:93]
	v_mul_f32_e32 v211, v28, v28
	v_fmac_f32_e32 v211, v29, v29
	v_fmac_f32_e32 v211, v30, v30
	v_fmac_f32_e32 v211, v31, v31
	s_waitcnt vmcnt(33)
	v_add_f32_e32 v24, v24, v212
	v_add_f32_e32 v25, v25, v213
	v_add_f32_e32 v26, v26, v214
	v_add_f32_e32 v27, v27, v215
	global_store_dwordx4 v152, v[24:27], s[88:89] offset:64
	v_cvt_pk_bf16_f32 v212, v24, v25
	v_cvt_pk_bf16_f32 v213, v26, v27
	global_store_dwordx2 v153, v[212:213], s[92:93] offset:32
	v_fmac_f32_e32 v211, v24, v24
	v_fmac_f32_e32 v211, v25, v25
	v_fmac_f32_e32 v211, v26, v26
	v_fmac_f32_e32 v211, v27, v27
	s_waitcnt vmcnt(32)
	v_add_f32_e32 v20, v20, v148
	v_add_f32_e32 v21, v21, v149
	v_add_f32_e32 v22, v22, v150
	v_add_f32_e32 v23, v23, v151
	global_store_dwordx4 v152, v[20:23], s[88:89] offset:512
	v_cvt_pk_bf16_f32 v148, v20, v21
	v_cvt_pk_bf16_f32 v149, v22, v23
	global_store_dwordx2 v153, v[148:149], s[92:93] offset:256
	v_fmac_f32_e32 v211, v20, v20
	v_fmac_f32_e32 v211, v21, v21
	v_fmac_f32_e32 v211, v22, v22
	v_fmac_f32_e32 v211, v23, v23
	s_waitcnt vmcnt(31)
	v_add_f32_e32 v16, v16, v160
	v_add_f32_e32 v17, v17, v161
	v_add_f32_e32 v18, v18, v162
	v_add_f32_e32 v19, v19, v163
	global_store_dwordx4 v152, v[16:19], s[88:89] offset:576
	v_cvt_pk_bf16_f32 v160, v16, v17
	v_cvt_pk_bf16_f32 v161, v18, v19
	global_store_dwordx2 v153, v[160:161], s[92:93] offset:288
	v_fmac_f32_e32 v211, v16, v16
	v_fmac_f32_e32 v211, v17, v17
	v_fmac_f32_e32 v211, v18, v18
	v_fmac_f32_e32 v211, v19, v19
	s_nop 0
	ds_bpermute_b32 v219, v216, v211
	s_waitcnt lgkmcnt(0)
	v_add_f32_e32 v211, v211, v219
	s_nop 0
	ds_bpermute_b32 v219, v217, v211
	s_waitcnt lgkmcnt(0)
	v_add_f32_e32 v211, v211, v219
	v_cmp_eq_u32_e32 vcc, 0, v218
	s_and_saveexec_b64 s[98:99], vcc
	global_store_dword v210, v211, s[100:101]
	s_mov_b64 exec, s[98:99]
	s_add_u32 s88, s88, 0x10000
	s_addc_u32 s89, s89, 0
	s_add_u32 s92, s92, 0x8000
	s_addc_u32 s93, s93, 0
	s_add_u32 s100, s100, 0x400
	s_addc_u32 s101, s101, 0
	s_waitcnt vmcnt(31)
	v_add_f32_e32 v12, v12, v164
	v_add_f32_e32 v13, v13, v165
	v_add_f32_e32 v14, v14, v166
	v_add_f32_e32 v15, v15, v167
	global_store_dwordx4 v152, v[12:15], s[88:89]
	v_cvt_pk_bf16_f32 v164, v12, v13
	v_cvt_pk_bf16_f32 v165, v14, v15
	global_store_dwordx2 v153, v[164:165], s[92:93]
	v_mul_f32_e32 v211, v12, v12
	v_fmac_f32_e32 v211, v13, v13
	v_fmac_f32_e32 v211, v14, v14
	v_fmac_f32_e32 v211, v15, v15
	s_waitcnt vmcnt(29)
	v_add_f32_e32 v8, v8, v168
	v_add_f32_e32 v9, v9, v169
	v_add_f32_e32 v10, v10, v170
	v_add_f32_e32 v11, v11, v171
	global_store_dwordx4 v152, v[8:11], s[88:89] offset:64
	v_cvt_pk_bf16_f32 v168, v8, v9
	v_cvt_pk_bf16_f32 v169, v10, v11
	global_store_dwordx2 v153, v[168:169], s[92:93] offset:32
	v_fmac_f32_e32 v211, v8, v8
	v_fmac_f32_e32 v211, v9, v9
	v_fmac_f32_e32 v211, v10, v10
	v_fmac_f32_e32 v211, v11, v11
	s_waitcnt vmcnt(28)
	v_add_f32_e32 v4, v4, v172
	v_add_f32_e32 v5, v5, v173
	v_add_f32_e32 v6, v6, v174
	v_add_f32_e32 v7, v7, v175
	global_store_dwordx4 v152, v[4:7], s[88:89] offset:512
	v_cvt_pk_bf16_f32 v172, v4, v5
	v_cvt_pk_bf16_f32 v173, v6, v7
	global_store_dwordx2 v153, v[172:173], s[92:93] offset:256
	v_fmac_f32_e32 v211, v4, v4
	v_fmac_f32_e32 v211, v5, v5
	v_fmac_f32_e32 v211, v6, v6
	v_fmac_f32_e32 v211, v7, v7
	s_waitcnt vmcnt(27)
	v_add_f32_e32 v0, v0, v176
	v_add_f32_e32 v1, v1, v177
	v_add_f32_e32 v2, v2, v178
	v_add_f32_e32 v3, v3, v179
	global_store_dwordx4 v152, v[0:3], s[88:89] offset:576
	v_cvt_pk_bf16_f32 v176, v0, v1
	v_cvt_pk_bf16_f32 v177, v2, v3
	global_store_dwordx2 v153, v[176:177], s[92:93] offset:288
	v_fmac_f32_e32 v211, v0, v0
	v_fmac_f32_e32 v211, v1, v1
	v_fmac_f32_e32 v211, v2, v2
	v_fmac_f32_e32 v211, v3, v3
	s_nop 0
	ds_bpermute_b32 v219, v216, v211
	s_waitcnt lgkmcnt(0)
	v_add_f32_e32 v211, v211, v219
	s_nop 0
	ds_bpermute_b32 v219, v217, v211
	s_waitcnt lgkmcnt(0)
	v_add_f32_e32 v211, v211, v219
	v_cmp_eq_u32_e32 vcc, 0, v218
	s_and_saveexec_b64 s[98:99], vcc
	global_store_dword v210, v211, s[100:101]
	s_mov_b64 exec, s[98:99]
	s_and_b64 vcc, exec, s[12:13]
	s_mov_b64 s[12:13], -1
	s_cbranch_vccnz .LBB0_997
	s_andn2_b64 vcc, exec, s[26:27]
	s_cbranch_vccnz .LBB0_996
	s_barrier
	s_branch .LBB0_996

.LBB0_1286:
	v_lshrrev_b32_e32 v132, 6, v206
	v_and_b32_e32 v143, 63, v206
	v_lshrrev_b32_e32 v142, 2, v132
	v_and_b32_e32 v132, 3, v132
	v_lshlrev_b32_e32 v142, 6, v142
	v_lshrrev_b32_e32 v214, 4, v143
	v_and_b32_e32 v215, 15, v143
	v_xor_b32_e32 v212, 16, v143
	v_xor_b32_e32 v213, 32, v143
	v_lshlrev_b32_e32 v212, 2, v212
	v_lshlrev_b32_e32 v213, 2, v213
	v_add_u32_e32 v142, v142, v215
	v_lshlrev_b32_e32 v143, 5, v132
	v_lshl_add_u32 v143, v214, 2, v143
	s_lshl_b32 vcc_lo, s24, 8
	v_add_u32_e32 v142, vcc_lo, v142
	s_lshl_b32 vcc_lo, s20, 8
	v_add_u32_e32 v143, vcc_lo, v143
	v_lshlrev_b32_e32 v148, 12, v142
	v_lshl_add_u32 v148, v143, 2, v148
	v_lshlrev_b32_e32 v149, 11, v142
	v_lshl_add_u32 v149, v143, 1, v149
	s_lshl_b32 vcc_lo, s20, 2
	v_add_u32_e32 v132, vcc_lo, v132
	v_lshlrev_b32_e32 v210, 6, v142
	v_lshl_add_u32 v210, v132, 2, v210
	s_mov_b32 s86, s94
	s_mov_b32 s87, s95
	s_mov_b32 s88, s94
	s_mov_b32 s89, s95
	s_add_u32 s92, s96, 0x9e00000
	s_addc_u32 s93, s97, 0
	s_add_u32 s100, s96, 0x5000000
	s_addc_u32 s101, s97, 0
	global_load_dwordx4 v[144:147], v148, s[86:87]
	global_load_dwordx4 v[156:159], v148, s[86:87] offset:64
	global_load_dwordx4 v[160:163], v148, s[86:87] offset:512
	global_load_dwordx4 v[164:167], v148, s[86:87] offset:576
	s_add_u32 s86, s86, 0x10000
	s_addc_u32 s87, s87, 0
	global_load_dwordx4 v[168:171], v148, s[86:87]
	global_load_dwordx4 v[172:175], v148, s[86:87] offset:64
	global_load_dwordx4 v[176:179], v148, s[86:87] offset:512
	global_load_dwordx4 v[180:183], v148, s[86:87] offset:576
	s_add_u32 s86, s86, 0x10000
	s_addc_u32 s87, s87, 0
	global_load_dwordx4 v[184:187], v148, s[86:87]
	global_load_dwordx4 v[188:191], v148, s[86:87] offset:64
	global_load_dwordx4 v[192:195], v148, s[86:87] offset:512
	global_load_dwordx4 v[196:199], v148, s[86:87] offset:576
	s_add_u32 s86, s86, 0x10000
	s_addc_u32 s87, s87, 0
	global_load_dwordx4 v[200:203], v148, s[86:87]
	s_waitcnt vmcnt(12)
	v_add_f32_e32 v124, v124, v144
	v_add_f32_e32 v125, v125, v145
	v_add_f32_e32 v126, v126, v146
	v_add_f32_e32 v127, v127, v147
	global_store_dwordx4 v148, v[124:127], s[88:89]
	v_cvt_pk_bf16_f32 v144, v124, v125
	v_cvt_pk_bf16_f32 v145, v126, v127
	global_store_dwordx2 v149, v[144:145], s[92:93]
	v_mul_f32_e32 v211, v124, v124
	v_fmac_f32_e32 v211, v125, v125
	v_fmac_f32_e32 v211, v126, v126
	v_fmac_f32_e32 v211, v127, v127
	global_load_dwordx4 v[144:147], v148, s[86:87] offset:64
	s_waitcnt vmcnt(14)
	v_add_f32_e32 v120, v120, v156
	v_add_f32_e32 v121, v121, v157
	v_add_f32_e32 v122, v122, v158
	v_add_f32_e32 v123, v123, v159
	global_store_dwordx4 v148, v[120:123], s[88:89] offset:64
	v_cvt_pk_bf16_f32 v156, v120, v121
	v_cvt_pk_bf16_f32 v157, v122, v123
	global_store_dwordx2 v149, v[156:157], s[92:93] offset:32
	v_fmac_f32_e32 v211, v120, v120
	v_fmac_f32_e32 v211, v121, v121
	v_fmac_f32_e32 v211, v122, v122
	v_fmac_f32_e32 v211, v123, v123
	global_load_dwordx4 v[156:159], v148, s[86:87] offset:512
	s_waitcnt vmcnt(16)
	v_add_f32_e32 v116, v116, v160
	v_add_f32_e32 v117, v117, v161
	v_add_f32_e32 v118, v118, v162
	v_add_f32_e32 v119, v119, v163
	global_store_dwordx4 v148, v[116:119], s[88:89] offset:512
	v_cvt_pk_bf16_f32 v160, v116, v117
	v_cvt_pk_bf16_f32 v161, v118, v119
	global_store_dwordx2 v149, v[160:161], s[92:93] offset:256
	v_fmac_f32_e32 v211, v116, v116
	v_fmac_f32_e32 v211, v117, v117
	v_fmac_f32_e32 v211, v118, v118
	v_fmac_f32_e32 v211, v119, v119
	global_load_dwordx4 v[160:163], v148, s[86:87] offset:576
	s_waitcnt vmcnt(18)
	v_add_f32_e32 v112, v112, v164
	v_add_f32_e32 v113, v113, v165
	v_add_f32_e32 v114, v114, v166
	v_add_f32_e32 v115, v115, v167
	global_store_dwordx4 v148, v[112:115], s[88:89] offset:576
	v_cvt_pk_bf16_f32 v164, v112, v113
	v_cvt_pk_bf16_f32 v165, v114, v115
	global_store_dwordx2 v149, v[164:165], s[92:93] offset:288
	v_fmac_f32_e32 v211, v112, v112
	v_fmac_f32_e32 v211, v113, v113
	v_fmac_f32_e32 v211, v114, v114
	v_fmac_f32_e32 v211, v115, v115
	s_add_u32 s86, s86, 0x50000
	s_addc_u32 s87, s87, 0
	global_load_dwordx4 v[164:167], v148, s[86:87]
	s_nop 0
	ds_bpermute_b32 v215, v212, v211
	s_waitcnt lgkmcnt(0)
	v_add_f32_e32 v211, v211, v215
	s_nop 0
	ds_bpermute_b32 v215, v213, v211
	s_waitcnt lgkmcnt(0)
	v_add_f32_e32 v211, v211, v215
	v_cmp_eq_u32_e32 vcc, 0, v214
	s_and_saveexec_b64 s[98:99], vcc
	global_store_dword v210, v211, s[100:101]
	s_mov_b64 exec, s[98:99]
	s_add_u32 s88, s88, 0x10000
	s_addc_u32 s89, s89, 0
	s_add_u32 s92, s92, 0x8000
	s_addc_u32 s93, s93, 0
	s_add_u32 s100, s100, 0x400
	s_addc_u32 s101, s101, 0
	s_waitcnt vmcnt(21)
	v_add_f32_e32 v108, v108, v168
	v_add_f32_e32 v109, v109, v169
	v_add_f32_e32 v110, v110, v170
	v_add_f32_e32 v111, v111, v171
	global_store_dwordx4 v148, v[108:111], s[88:89]
	v_cvt_pk_bf16_f32 v168, v108, v109
	v_cvt_pk_bf16_f32 v169, v110, v111
	global_store_dwordx2 v149, v[168:169], s[92:93]
	v_mul_f32_e32 v211, v108, v108
	v_fmac_f32_e32 v211, v109, v109
	v_fmac_f32_e32 v211, v110, v110
	v_fmac_f32_e32 v211, v111, v111
	global_load_dwordx4 v[168:171], v148, s[86:87] offset:64
	s_waitcnt vmcnt(23)
	v_add_f32_e32 v104, v104, v172
	v_add_f32_e32 v105, v105, v173
	v_add_f32_e32 v106, v106, v174
	v_add_f32_e32 v107, v107, v175
	global_store_dwordx4 v148, v[104:107], s[88:89] offset:64
	v_cvt_pk_bf16_f32 v172, v104, v105
	v_cvt_pk_bf16_f32 v173, v106, v107
	global_store_dwordx2 v149, v[172:173], s[92:93] offset:32
	v_fmac_f32_e32 v211, v104, v104
	v_fmac_f32_e32 v211, v105, v105
	v_fmac_f32_e32 v211, v106, v106
	v_fmac_f32_e32 v211, v107, v107
	global_load_dwordx4 v[172:175], v148, s[86:87] offset:512
	s_waitcnt vmcnt(25)
	v_add_f32_e32 v100, v100, v176
	v_add_f32_e32 v101, v101, v177
	v_add_f32_e32 v102, v102, v178
	v_add_f32_e32 v103, v103, v179
	global_store_dwordx4 v148, v[100:103], s[88:89] offset:512
	v_cvt_pk_bf16_f32 v176, v100, v101
	v_cvt_pk_bf16_f32 v177, v102, v103
	global_store_dwordx2 v149, v[176:177], s[92:93] offset:256
	v_fmac_f32_e32 v211, v100, v100
	v_fmac_f32_e32 v211, v101, v101
	v_fmac_f32_e32 v211, v102, v102
	v_fmac_f32_e32 v211, v103, v103
	global_load_dwordx4 v[176:179], v148, s[86:87] offset:576
	s_waitcnt vmcnt(27)
	v_add_f32_e32 v96, v96, v180
	v_add_f32_e32 v97, v97, v181
	v_add_f32_e32 v98, v98, v182
	v_add_f32_e32 v99, v99, v183
	global_store_dwordx4 v148, v[96:99], s[88:89] offset:576
	v_cvt_pk_bf16_f32 v180, v96, v97
	v_cvt_pk_bf16_f32 v181, v98, v99
	global_store_dwordx2 v149, v[180:181], s[92:93] offset:288
	v_fmac_f32_e32 v211, v96, v96
	v_fmac_f32_e32 v211, v97, v97
	v_fmac_f32_e32 v211, v98, v98
	v_fmac_f32_e32 v211, v99, v99
	s_add_u32 s86, s86, 0x10000
	s_addc_u32 s87, s87, 0
	global_load_dwordx4 v[180:183], v148, s[86:87]
	s_nop 0
	ds_bpermute_b32 v215, v212, v211
	s_waitcnt lgkmcnt(0)
	v_add_f32_e32 v211, v211, v215
	s_nop 0
	ds_bpermute_b32 v215, v213, v211
	s_waitcnt lgkmcnt(0)
	v_add_f32_e32 v211, v211, v215
	v_cmp_eq_u32_e32 vcc, 0, v214
	s_and_saveexec_b64 s[98:99], vcc
	global_store_dword v210, v211, s[100:101]
	s_mov_b64 exec, s[98:99]
	s_add_u32 s88, s88, 0x10000
	s_addc_u32 s89, s89, 0
	s_add_u32 s92, s92, 0x8000
	s_addc_u32 s93, s93, 0
	s_add_u32 s100, s100, 0x400
	s_addc_u32 s101, s101, 0
	s_waitcnt vmcnt(30)
	v_add_f32_e32 v92, v92, v184
	v_add_f32_e32 v93, v93, v185
	v_add_f32_e32 v94, v94, v186
	v_add_f32_e32 v95, v95, v187
	global_store_dwordx4 v148, v[92:95], s[88:89]
	v_cvt_pk_bf16_f32 v184, v92, v93
	v_cvt_pk_bf16_f32 v185, v94, v95
	global_store_dwordx2 v149, v[184:185], s[92:93]
	v_mul_f32_e32 v211, v92, v92
	v_fmac_f32_e32 v211, v93, v93
	v_fmac_f32_e32 v211, v94, v94
	v_fmac_f32_e32 v211, v95, v95
	global_load_dwordx4 v[184:187], v148, s[86:87] offset:64
	s_waitcnt vmcnt(32)
	v_add_f32_e32 v88, v88, v188
	v_add_f32_e32 v89, v89, v189
	v_add_f32_e32 v90, v90, v190
	v_add_f32_e32 v91, v91, v191
	global_store_dwordx4 v148, v[88:91], s[88:89] offset:64
	v_cvt_pk_bf16_f32 v188, v88, v89
	v_cvt_pk_bf16_f32 v189, v90, v91
	global_store_dwordx2 v149, v[188:189], s[92:93] offset:32
	v_fmac_f32_e32 v211, v88, v88
	v_fmac_f32_e32 v211, v89, v89
	v_fmac_f32_e32 v211, v90, v90
	v_fmac_f32_e32 v211, v91, v91
	global_load_dwordx4 v[188:191], v148, s[86:87] offset:512
	s_waitcnt vmcnt(34)
	v_add_f32_e32 v84, v84, v192
	v_add_f32_e32 v85, v85, v193
	v_add_f32_e32 v86, v86, v194
	v_add_f32_e32 v87, v87, v195
	global_store_dwordx4 v148, v[84:87], s[88:89] offset:512
	v_cvt_pk_bf16_f32 v192, v84, v85
	v_cvt_pk_bf16_f32 v193, v86, v87
	global_store_dwordx2 v149, v[192:193], s[92:93] offset:256
	v_fmac_f32_e32 v211, v84, v84
	v_fmac_f32_e32 v211, v85, v85
	v_fmac_f32_e32 v211, v86, v86
	v_fmac_f32_e32 v211, v87, v87
	global_load_dwordx4 v[192:195], v148, s[86:87] offset:576
	s_waitcnt vmcnt(36)
	v_add_f32_e32 v80, v80, v196
	v_add_f32_e32 v81, v81, v197
	v_add_f32_e32 v82, v82, v198
	v_add_f32_e32 v83, v83, v199
	global_store_dwordx4 v148, v[80:83], s[88:89] offset:576
	v_cvt_pk_bf16_f32 v196, v80, v81
	v_cvt_pk_bf16_f32 v197, v82, v83
	global_store_dwordx2 v149, v[196:197], s[92:93] offset:288
	v_fmac_f32_e32 v211, v80, v80
	v_fmac_f32_e32 v211, v81, v81
	v_fmac_f32_e32 v211, v82, v82
	v_fmac_f32_e32 v211, v83, v83
	s_add_u32 s86, s86, 0x10000
	s_addc_u32 s87, s87, 0
	global_load_dwordx4 v[196:199], v148, s[86:87]
	s_nop 0
	ds_bpermute_b32 v215, v212, v211
	s_waitcnt lgkmcnt(0)
	v_add_f32_e32 v211, v211, v215
	s_nop 0
	ds_bpermute_b32 v215, v213, v211
	s_waitcnt lgkmcnt(0)
	v_add_f32_e32 v211, v211, v215
	v_cmp_eq_u32_e32 vcc, 0, v214
	s_and_saveexec_b64 s[98:99], vcc
	global_store_dword v210, v211, s[100:101]
	s_mov_b64 exec, s[98:99]
	s_add_u32 s88, s88, 0x10000
	s_addc_u32 s89, s89, 0
	s_add_u32 s92, s92, 0x8000
	s_addc_u32 s93, s93, 0
	s_add_u32 s100, s100, 0x400
	s_addc_u32 s101, s101, 0
	s_waitcnt vmcnt(39)
	v_add_f32_e32 v76, v76, v200
	v_add_f32_e32 v77, v77, v201
	v_add_f32_e32 v78, v78, v202
	v_add_f32_e32 v79, v79, v203
	global_store_dwordx4 v148, v[76:79], s[88:89]
	v_cvt_pk_bf16_f32 v200, v76, v77
	v_cvt_pk_bf16_f32 v201, v78, v79
	global_store_dwordx2 v149, v[200:201], s[92:93]
	v_mul_f32_e32 v211, v76, v76
	v_fmac_f32_e32 v211, v77, v77
	v_fmac_f32_e32 v211, v78, v78
	v_fmac_f32_e32 v211, v79, v79
	global_load_dwordx4 v[200:203], v148, s[86:87] offset:64
	s_waitcnt vmcnt(39)
	v_add_f32_e32 v72, v72, v144
	v_add_f32_e32 v73, v73, v145
	v_add_f32_e32 v74, v74, v146
	v_add_f32_e32 v75, v75, v147
	global_store_dwordx4 v148, v[72:75], s[88:89] offset:64
	v_cvt_pk_bf16_f32 v144, v72, v73
	v_cvt_pk_bf16_f32 v145, v74, v75
	global_store_dwordx2 v149, v[144:145], s[92:93] offset:32
	v_fmac_f32_e32 v211, v72, v72
	v_fmac_f32_e32 v211, v73, v73
	v_fmac_f32_e32 v211, v74, v74
	v_fmac_f32_e32 v211, v75, v75
	global_load_dwordx4 v[144:147], v148, s[86:87] offset:512
	s_waitcnt vmcnt(39)
	v_add_f32_e32 v68, v68, v156
	v_add_f32_e32 v69, v69, v157
	v_add_f32_e32 v70, v70, v158
	v_add_f32_e32 v71, v71, v159
	global_store_dwordx4 v148, v[68:71], s[88:89] offset:512
	v_cvt_pk_bf16_f32 v156, v68, v69
	v_cvt_pk_bf16_f32 v157, v70, v71
	global_store_dwordx2 v149, v[156:157], s[92:93] offset:256
	v_fmac_f32_e32 v211, v68, v68
	v_fmac_f32_e32 v211, v69, v69
	v_fmac_f32_e32 v211, v70, v70
	v_fmac_f32_e32 v211, v71, v71
	global_load_dwordx4 v[156:159], v148, s[86:87] offset:576
	s_waitcnt vmcnt(39)
	v_add_f32_e32 v64, v64, v160
	v_add_f32_e32 v65, v65, v161
	v_add_f32_e32 v66, v66, v162
	v_add_f32_e32 v67, v67, v163
	global_store_dwordx4 v148, v[64:67], s[88:89] offset:576
	v_cvt_pk_bf16_f32 v160, v64, v65
	v_cvt_pk_bf16_f32 v161, v66, v67
	global_store_dwordx2 v149, v[160:161], s[92:93] offset:288
	v_fmac_f32_e32 v211, v64, v64
	v_fmac_f32_e32 v211, v65, v65
	v_fmac_f32_e32 v211, v66, v66
	v_fmac_f32_e32 v211, v67, v67
	s_add_u32 s86, s86, 0x10000
	s_addc_u32 s87, s87, 0
	global_load_dwordx4 v[160:163], v148, s[86:87]
	s_nop 0
	ds_bpermute_b32 v215, v212, v211
	s_waitcnt lgkmcnt(0)
	v_add_f32_e32 v211, v211, v215
	s_nop 0
	ds_bpermute_b32 v215, v213, v211
	s_waitcnt lgkmcnt(0)
	v_add_f32_e32 v211, v211, v215
	v_cmp_eq_u32_e32 vcc, 0, v214
	s_and_saveexec_b64 s[98:99], vcc
	global_store_dword v210, v211, s[100:101]
	s_mov_b64 exec, s[98:99]
	s_add_u32 s88, s88, 0x50000
	s_addc_u32 s89, s89, 0
	s_add_u32 s92, s92, 0x28000
	s_addc_u32 s93, s93, 0
	s_add_u32 s100, s100, 0x1400
	s_addc_u32 s101, s101, 0
	s_waitcnt vmcnt(40)
	v_add_f32_e32 v60, v60, v164
	v_add_f32_e32 v61, v61, v165
	v_add_f32_e32 v62, v62, v166
	v_add_f32_e32 v63, v63, v167
	global_store_dwordx4 v148, v[60:63], s[88:89]
	v_cvt_pk_bf16_f32 v164, v60, v61
	v_cvt_pk_bf16_f32 v165, v62, v63
	global_store_dwordx2 v149, v[164:165], s[92:93]
	v_mul_f32_e32 v211, v60, v60
	v_fmac_f32_e32 v211, v61, v61
	v_fmac_f32_e32 v211, v62, v62
	v_fmac_f32_e32 v211, v63, v63
	global_load_dwordx4 v[164:167], v148, s[86:87] offset:64
	s_waitcnt vmcnt(39)
	v_add_f32_e32 v56, v56, v168
	v_add_f32_e32 v57, v57, v169
	v_add_f32_e32 v58, v58, v170
	v_add_f32_e32 v59, v59, v171
	global_store_dwordx4 v148, v[56:59], s[88:89] offset:64
	v_cvt_pk_bf16_f32 v168, v56, v57
	v_cvt_pk_bf16_f32 v169, v58, v59
	global_store_dwordx2 v149, v[168:169], s[92:93] offset:32
	v_fmac_f32_e32 v211, v56, v56
	v_fmac_f32_e32 v211, v57, v57
	v_fmac_f32_e32 v211, v58, v58
	v_fmac_f32_e32 v211, v59, v59
	global_load_dwordx4 v[168:171], v148, s[86:87] offset:512
	s_waitcnt vmcnt(39)
	v_add_f32_e32 v52, v52, v172
	v_add_f32_e32 v53, v53, v173
	v_add_f32_e32 v54, v54, v174
	v_add_f32_e32 v55, v55, v175
	global_store_dwordx4 v148, v[52:55], s[88:89] offset:512
	v_cvt_pk_bf16_f32 v172, v52, v53
	v_cvt_pk_bf16_f32 v173, v54, v55
	global_store_dwordx2 v149, v[172:173], s[92:93] offset:256
	v_fmac_f32_e32 v211, v52, v52
	v_fmac_f32_e32 v211, v53, v53
	v_fmac_f32_e32 v211, v54, v54
	v_fmac_f32_e32 v211, v55, v55
	global_load_dwordx4 v[172:175], v148, s[86:87] offset:576
	s_waitcnt vmcnt(39)
	v_add_f32_e32 v48, v48, v176
	v_add_f32_e32 v49, v49, v177
	v_add_f32_e32 v50, v50, v178
	v_add_f32_e32 v51, v51, v179
	global_store_dwordx4 v148, v[48:51], s[88:89] offset:576
	v_cvt_pk_bf16_f32 v176, v48, v49
	v_cvt_pk_bf16_f32 v177, v50, v51
	global_store_dwordx2 v149, v[176:177], s[92:93] offset:288
	v_fmac_f32_e32 v211, v48, v48
	v_fmac_f32_e32 v211, v49, v49
	v_fmac_f32_e32 v211, v50, v50
	v_fmac_f32_e32 v211, v51, v51
	s_nop 0
	ds_bpermute_b32 v215, v212, v211
	s_waitcnt lgkmcnt(0)
	v_add_f32_e32 v211, v211, v215
	s_nop 0
	ds_bpermute_b32 v215, v213, v211
	s_waitcnt lgkmcnt(0)
	v_add_f32_e32 v211, v211, v215
	v_cmp_eq_u32_e32 vcc, 0, v214
	s_and_saveexec_b64 s[98:99], vcc
	global_store_dword v210, v211, s[100:101]
	s_mov_b64 exec, s[98:99]
	s_add_u32 s88, s88, 0x10000
	s_addc_u32 s89, s89, 0
	s_add_u32 s92, s92, 0x8000
	s_addc_u32 s93, s93, 0
	s_add_u32 s100, s100, 0x400
	s_addc_u32 s101, s101, 0
	s_waitcnt vmcnt(39)
	v_add_f32_e32 v44, v44, v180
	v_add_f32_e32 v45, v45, v181
	v_add_f32_e32 v46, v46, v182
	v_add_f32_e32 v47, v47, v183
	global_store_dwordx4 v148, v[44:47], s[88:89]
	v_cvt_pk_bf16_f32 v180, v44, v45
	v_cvt_pk_bf16_f32 v181, v46, v47
	global_store_dwordx2 v149, v[180:181], s[92:93]
	v_mul_f32_e32 v211, v44, v44
	v_fmac_f32_e32 v211, v45, v45
	v_fmac_f32_e32 v211, v46, v46
	v_fmac_f32_e32 v211, v47, v47
	s_waitcnt vmcnt(37)
	v_add_f32_e32 v40, v40, v184
	v_add_f32_e32 v41, v41, v185
	v_add_f32_e32 v42, v42, v186
	v_add_f32_e32 v43, v43, v187
	global_store_dwordx4 v148, v[40:43], s[88:89] offset:64
	v_cvt_pk_bf16_f32 v184, v40, v41
	v_cvt_pk_bf16_f32 v185, v42, v43
	global_store_dwordx2 v149, v[184:185], s[92:93] offset:32
	v_fmac_f32_e32 v211, v40, v40
	v_fmac_f32_e32 v211, v41, v41
	v_fmac_f32_e32 v211, v42, v42
	v_fmac_f32_e32 v211, v43, v43
	s_waitcnt vmcnt(36)
	v_add_f32_e32 v36, v36, v188
	v_add_f32_e32 v37, v37, v189
	v_add_f32_e32 v38, v38, v190
	v_add_f32_e32 v39, v39, v191
	global_store_dwordx4 v148, v[36:39], s[88:89] offset:512
	v_cvt_pk_bf16_f32 v188, v36, v37
	v_cvt_pk_bf16_f32 v189, v38, v39
	global_store_dwordx2 v149, v[188:189], s[92:93] offset:256
	v_fmac_f32_e32 v211, v36, v36
	v_fmac_f32_e32 v211, v37, v37
	v_fmac_f32_e32 v211, v38, v38
	v_fmac_f32_e32 v211, v39, v39
	s_waitcnt vmcnt(35)
	v_add_f32_e32 v32, v32, v192
	v_add_f32_e32 v33, v33, v193
	v_add_f32_e32 v34, v34, v194
	v_add_f32_e32 v35, v35, v195
	global_store_dwordx4 v148, v[32:35], s[88:89] offset:576
	v_cvt_pk_bf16_f32 v192, v32, v33
	v_cvt_pk_bf16_f32 v193, v34, v35
	global_store_dwordx2 v149, v[192:193], s[92:93] offset:288
	v_fmac_f32_e32 v211, v32, v32
	v_fmac_f32_e32 v211, v33, v33
	v_fmac_f32_e32 v211, v34, v34
	v_fmac_f32_e32 v211, v35, v35
	s_nop 0
	ds_bpermute_b32 v215, v212, v211
	s_waitcnt lgkmcnt(0)
	v_add_f32_e32 v211, v211, v215
	s_nop 0
	ds_bpermute_b32 v215, v213, v211
	s_waitcnt lgkmcnt(0)
	v_add_f32_e32 v211, v211, v215
	v_cmp_eq_u32_e32 vcc, 0, v214
	s_and_saveexec_b64 s[98:99], vcc
	global_store_dword v210, v211, s[100:101]
	s_mov_b64 exec, s[98:99]
	s_add_u32 s88, s88, 0x10000
	s_addc_u32 s89, s89, 0
	s_add_u32 s92, s92, 0x8000
	s_addc_u32 s93, s93, 0
	s_add_u32 s100, s100, 0x400
	s_addc_u32 s101, s101, 0
	s_waitcnt vmcnt(35)
	v_add_f32_e32 v28, v28, v196
	v_add_f32_e32 v29, v29, v197
	v_add_f32_e32 v30, v30, v198
	v_add_f32_e32 v31, v31, v199
	global_store_dwordx4 v148, v[28:31], s[88:89]
	v_cvt_pk_bf16_f32 v196, v28, v29
	v_cvt_pk_bf16_f32 v197, v30, v31
	global_store_dwordx2 v149, v[196:197], s[92:93]
	v_mul_f32_e32 v211, v28, v28
	v_fmac_f32_e32 v211, v29, v29
	v_fmac_f32_e32 v211, v30, v30
	v_fmac_f32_e32 v211, v31, v31
	s_waitcnt vmcnt(33)
	v_add_f32_e32 v24, v24, v200
	v_add_f32_e32 v25, v25, v201
	v_add_f32_e32 v26, v26, v202
	v_add_f32_e32 v27, v27, v203
	global_store_dwordx4 v148, v[24:27], s[88:89] offset:64
	v_cvt_pk_bf16_f32 v200, v24, v25
	v_cvt_pk_bf16_f32 v201, v26, v27
	global_store_dwordx2 v149, v[200:201], s[92:93] offset:32
	v_fmac_f32_e32 v211, v24, v24
	v_fmac_f32_e32 v211, v25, v25
	v_fmac_f32_e32 v211, v26, v26
	v_fmac_f32_e32 v211, v27, v27
	s_waitcnt vmcnt(32)
	v_add_f32_e32 v20, v20, v144
	v_add_f32_e32 v21, v21, v145
	v_add_f32_e32 v22, v22, v146
	v_add_f32_e32 v23, v23, v147
	global_store_dwordx4 v148, v[20:23], s[88:89] offset:512
	v_cvt_pk_bf16_f32 v144, v20, v21
	v_cvt_pk_bf16_f32 v145, v22, v23
	global_store_dwordx2 v149, v[144:145], s[92:93] offset:256
	v_fmac_f32_e32 v211, v20, v20
	v_fmac_f32_e32 v211, v21, v21
	v_fmac_f32_e32 v211, v22, v22
	v_fmac_f32_e32 v211, v23, v23
	s_waitcnt vmcnt(31)
	v_add_f32_e32 v16, v16, v156
	v_add_f32_e32 v17, v17, v157
	v_add_f32_e32 v18, v18, v158
	v_add_f32_e32 v19, v19, v159
	global_store_dwordx4 v148, v[16:19], s[88:89] offset:576
	v_cvt_pk_bf16_f32 v156, v16, v17
	v_cvt_pk_bf16_f32 v157, v18, v19
	global_store_dwordx2 v149, v[156:157], s[92:93] offset:288
	v_fmac_f32_e32 v211, v16, v16
	v_fmac_f32_e32 v211, v17, v17
	v_fmac_f32_e32 v211, v18, v18
	v_fmac_f32_e32 v211, v19, v19
	s_nop 0
	ds_bpermute_b32 v215, v212, v211
	s_waitcnt lgkmcnt(0)
	v_add_f32_e32 v211, v211, v215
	s_nop 0
	ds_bpermute_b32 v215, v213, v211
	s_waitcnt lgkmcnt(0)
	v_add_f32_e32 v211, v211, v215
	v_cmp_eq_u32_e32 vcc, 0, v214
	s_and_saveexec_b64 s[98:99], vcc
	global_store_dword v210, v211, s[100:101]
	s_mov_b64 exec, s[98:99]
	s_add_u32 s88, s88, 0x10000
	s_addc_u32 s89, s89, 0
	s_add_u32 s92, s92, 0x8000
	s_addc_u32 s93, s93, 0
	s_add_u32 s100, s100, 0x400
	s_addc_u32 s101, s101, 0
	s_waitcnt vmcnt(31)
	v_add_f32_e32 v12, v12, v160
	v_add_f32_e32 v13, v13, v161
	v_add_f32_e32 v14, v14, v162
	v_add_f32_e32 v15, v15, v163
	global_store_dwordx4 v148, v[12:15], s[88:89]
	v_cvt_pk_bf16_f32 v160, v12, v13
	v_cvt_pk_bf16_f32 v161, v14, v15
	global_store_dwordx2 v149, v[160:161], s[92:93]
	v_mul_f32_e32 v211, v12, v12
	v_fmac_f32_e32 v211, v13, v13
	v_fmac_f32_e32 v211, v14, v14
	v_fmac_f32_e32 v211, v15, v15
	s_waitcnt vmcnt(29)
	v_add_f32_e32 v8, v8, v164
	v_add_f32_e32 v9, v9, v165
	v_add_f32_e32 v10, v10, v166
	v_add_f32_e32 v11, v11, v167
	global_store_dwordx4 v148, v[8:11], s[88:89] offset:64
	v_cvt_pk_bf16_f32 v164, v8, v9
	v_cvt_pk_bf16_f32 v165, v10, v11
	global_store_dwordx2 v149, v[164:165], s[92:93] offset:32
	v_fmac_f32_e32 v211, v8, v8
	v_fmac_f32_e32 v211, v9, v9
	v_fmac_f32_e32 v211, v10, v10
	v_fmac_f32_e32 v211, v11, v11
	s_waitcnt vmcnt(28)
	v_add_f32_e32 v4, v4, v168
	v_add_f32_e32 v5, v5, v169
	v_add_f32_e32 v6, v6, v170
	v_add_f32_e32 v7, v7, v171
	global_store_dwordx4 v148, v[4:7], s[88:89] offset:512
	v_cvt_pk_bf16_f32 v168, v4, v5
	v_cvt_pk_bf16_f32 v169, v6, v7
	global_store_dwordx2 v149, v[168:169], s[92:93] offset:256
	v_fmac_f32_e32 v211, v4, v4
	v_fmac_f32_e32 v211, v5, v5
	v_fmac_f32_e32 v211, v6, v6
	v_fmac_f32_e32 v211, v7, v7
	s_waitcnt vmcnt(27)
	v_add_f32_e32 v0, v0, v172
	v_add_f32_e32 v1, v1, v173
	v_add_f32_e32 v2, v2, v174
	v_add_f32_e32 v3, v3, v175
	global_store_dwordx4 v148, v[0:3], s[88:89] offset:576
	v_cvt_pk_bf16_f32 v172, v0, v1
	v_cvt_pk_bf16_f32 v173, v2, v3
	global_store_dwordx2 v149, v[172:173], s[92:93] offset:288
	v_fmac_f32_e32 v211, v0, v0
	v_fmac_f32_e32 v211, v1, v1
	v_fmac_f32_e32 v211, v2, v2
	v_fmac_f32_e32 v211, v3, v3
	s_nop 0
	ds_bpermute_b32 v215, v212, v211
	s_waitcnt lgkmcnt(0)
	v_add_f32_e32 v211, v211, v215
	s_nop 0
	ds_bpermute_b32 v215, v213, v211
	s_waitcnt lgkmcnt(0)
	v_add_f32_e32 v211, v211, v215
	v_cmp_eq_u32_e32 vcc, 0, v214
	s_and_saveexec_b64 s[98:99], vcc
	global_store_dword v210, v211, s[100:101]
	s_mov_b64 exec, s[98:99]
	s_andn2_b64 vcc, exec, s[12:13]
	s_mov_b64 s[12:13], -1
	s_cbranch_vccnz .LBB0_1275
	s_andn2_b64 vcc, exec, s[26:27]
	s_cbranch_vccnz .LBB0_1274
	s_barrier
	s_branch .LBB0_1274

.LBB0_1492:
	v_lshrrev_b32_e32 v132, 6, v206
	v_and_b32_e32 v143, 63, v206
	v_lshrrev_b32_e32 v142, 2, v132
	v_and_b32_e32 v132, 3, v132
	v_lshlrev_b32_e32 v142, 6, v142
	v_lshrrev_b32_e32 v214, 4, v143
	v_and_b32_e32 v215, 15, v143
	v_xor_b32_e32 v212, 16, v143
	v_xor_b32_e32 v213, 32, v143
	v_lshlrev_b32_e32 v212, 2, v212
	v_lshlrev_b32_e32 v213, 2, v213
	v_add_u32_e32 v142, v142, v215
	v_lshlrev_b32_e32 v143, 5, v132
	v_lshl_add_u32 v143, v214, 2, v143
	s_lshl_b32 vcc_lo, s12, 8
	v_add_u32_e32 v142, vcc_lo, v142
	s_lshl_b32 vcc_lo, s49, 8
	v_add_u32_e32 v143, vcc_lo, v143
	v_lshlrev_b32_e32 v148, 12, v142
	v_lshl_add_u32 v148, v143, 2, v148
	v_lshlrev_b32_e32 v149, 11, v142
	v_lshl_add_u32 v149, v143, 1, v149
	s_lshl_b32 vcc_lo, s49, 2
	v_add_u32_e32 v132, vcc_lo, v132
	v_lshlrev_b32_e32 v210, 6, v142
	v_lshl_add_u32 v210, v132, 2, v210
	s_mov_b32 s86, s94
	s_mov_b32 s87, s95
	s_mov_b32 s88, s94
	s_mov_b32 s89, s95
	s_add_u32 s100, s96, 0x5500000
	s_addc_u32 s101, s97, 0
	global_load_dwordx4 v[144:147], v148, s[86:87]
	global_load_dwordx4 v[156:159], v148, s[86:87] offset:64
	global_load_dwordx4 v[160:163], v148, s[86:87] offset:512
	global_load_dwordx4 v[164:167], v148, s[86:87] offset:576
	s_add_u32 s86, s86, 0x10000
	s_addc_u32 s87, s87, 0
	global_load_dwordx4 v[168:171], v148, s[86:87]
	global_load_dwordx4 v[172:175], v148, s[86:87] offset:64
	global_load_dwordx4 v[176:179], v148, s[86:87] offset:512
	global_load_dwordx4 v[180:183], v148, s[86:87] offset:576
	s_add_u32 s86, s86, 0x10000
	s_addc_u32 s87, s87, 0
	global_load_dwordx4 v[184:187], v148, s[86:87]
	global_load_dwordx4 v[188:191], v148, s[86:87] offset:64
	global_load_dwordx4 v[192:195], v148, s[86:87] offset:512
	global_load_dwordx4 v[196:199], v148, s[86:87] offset:576
	s_add_u32 s86, s86, 0x10000
	s_addc_u32 s87, s87, 0
	global_load_dwordx4 v[200:203], v148, s[86:87]
	s_waitcnt vmcnt(12)
	v_fma_f32 v124, v124, 0.5, v144
	v_fma_f32 v125, v125, 0.5, v145
	v_fma_f32 v126, v126, 0.5, v146
	v_fma_f32 v127, v127, 0.5, v147
	global_store_dwordx4 v148, v[124:127], s[88:89]
	v_mul_f32_e32 v211, v124, v124
	v_fmac_f32_e32 v211, v125, v125
	v_fmac_f32_e32 v211, v126, v126
	v_fmac_f32_e32 v211, v127, v127
	global_load_dwordx4 v[144:147], v148, s[86:87] offset:64
	s_waitcnt vmcnt(13)
	v_fma_f32 v120, v120, 0.5, v156
	v_fma_f32 v121, v121, 0.5, v157
	v_fma_f32 v122, v122, 0.5, v158
	v_fma_f32 v123, v123, 0.5, v159
	global_store_dwordx4 v148, v[120:123], s[88:89] offset:64
	v_fmac_f32_e32 v211, v120, v120
	v_fmac_f32_e32 v211, v121, v121
	v_fmac_f32_e32 v211, v122, v122
	v_fmac_f32_e32 v211, v123, v123
	global_load_dwordx4 v[156:159], v148, s[86:87] offset:512
	s_waitcnt vmcnt(14)
	v_fma_f32 v116, v116, 0.5, v160
	v_fma_f32 v117, v117, 0.5, v161
	v_fma_f32 v118, v118, 0.5, v162
	v_fma_f32 v119, v119, 0.5, v163
	global_store_dwordx4 v148, v[116:119], s[88:89] offset:512
	v_fmac_f32_e32 v211, v116, v116
	v_fmac_f32_e32 v211, v117, v117
	v_fmac_f32_e32 v211, v118, v118
	v_fmac_f32_e32 v211, v119, v119
	global_load_dwordx4 v[160:163], v148, s[86:87] offset:576
	s_waitcnt vmcnt(15)
	v_fma_f32 v112, v112, 0.5, v164
	v_fma_f32 v113, v113, 0.5, v165
	v_fma_f32 v114, v114, 0.5, v166
	v_fma_f32 v115, v115, 0.5, v167
	global_store_dwordx4 v148, v[112:115], s[88:89] offset:576
	v_fmac_f32_e32 v211, v112, v112
	v_fmac_f32_e32 v211, v113, v113
	v_fmac_f32_e32 v211, v114, v114
	v_fmac_f32_e32 v211, v115, v115
	s_add_u32 s86, s86, 0x50000
	s_addc_u32 s87, s87, 0
	global_load_dwordx4 v[164:167], v148, s[86:87]
	s_nop 0
	ds_bpermute_b32 v215, v212, v211
	s_waitcnt lgkmcnt(0)
	v_add_f32_e32 v211, v211, v215
	s_nop 0
	ds_bpermute_b32 v215, v213, v211
	s_waitcnt lgkmcnt(0)
	v_add_f32_e32 v211, v211, v215
	v_cmp_eq_u32_e32 vcc, 0, v214
	s_and_saveexec_b64 s[98:99], vcc
	global_store_dword v210, v211, s[100:101]
	s_mov_b64 exec, s[98:99]
	s_add_u32 s88, s88, 0x10000
	s_addc_u32 s89, s89, 0
	s_add_u32 s100, s100, 0x400
	s_addc_u32 s101, s101, 0
	s_waitcnt vmcnt(17)
	v_fma_f32 v108, v108, 0.5, v168
	v_fma_f32 v109, v109, 0.5, v169
	v_fma_f32 v110, v110, 0.5, v170
	v_fma_f32 v111, v111, 0.5, v171
	global_store_dwordx4 v148, v[108:111], s[88:89]
	v_mul_f32_e32 v211, v108, v108
	v_fmac_f32_e32 v211, v109, v109
	v_fmac_f32_e32 v211, v110, v110
	v_fmac_f32_e32 v211, v111, v111
	global_load_dwordx4 v[168:171], v148, s[86:87] offset:64
	s_waitcnt vmcnt(18)
	v_fma_f32 v104, v104, 0.5, v172
	v_fma_f32 v105, v105, 0.5, v173
	v_fma_f32 v106, v106, 0.5, v174
	v_fma_f32 v107, v107, 0.5, v175
	global_store_dwordx4 v148, v[104:107], s[88:89] offset:64
	v_fmac_f32_e32 v211, v104, v104
	v_fmac_f32_e32 v211, v105, v105
	v_fmac_f32_e32 v211, v106, v106
	v_fmac_f32_e32 v211, v107, v107
	global_load_dwordx4 v[172:175], v148, s[86:87] offset:512
	s_waitcnt vmcnt(19)
	v_fma_f32 v100, v100, 0.5, v176
	v_fma_f32 v101, v101, 0.5, v177
	v_fma_f32 v102, v102, 0.5, v178
	v_fma_f32 v103, v103, 0.5, v179
	global_store_dwordx4 v148, v[100:103], s[88:89] offset:512
	v_fmac_f32_e32 v211, v100, v100
	v_fmac_f32_e32 v211, v101, v101
	v_fmac_f32_e32 v211, v102, v102
	v_fmac_f32_e32 v211, v103, v103
	global_load_dwordx4 v[176:179], v148, s[86:87] offset:576
	s_waitcnt vmcnt(20)
	v_fma_f32 v96, v96, 0.5, v180
	v_fma_f32 v97, v97, 0.5, v181
	v_fma_f32 v98, v98, 0.5, v182
	v_fma_f32 v99, v99, 0.5, v183
	global_store_dwordx4 v148, v[96:99], s[88:89] offset:576
	v_fmac_f32_e32 v211, v96, v96
	v_fmac_f32_e32 v211, v97, v97
	v_fmac_f32_e32 v211, v98, v98
	v_fmac_f32_e32 v211, v99, v99
	s_add_u32 s86, s86, 0x10000
	s_addc_u32 s87, s87, 0
	global_load_dwordx4 v[180:183], v148, s[86:87]
	s_nop 0
	ds_bpermute_b32 v215, v212, v211
	s_waitcnt lgkmcnt(0)
	v_add_f32_e32 v211, v211, v215
	s_nop 0
	ds_bpermute_b32 v215, v213, v211
	s_waitcnt lgkmcnt(0)
	v_add_f32_e32 v211, v211, v215
	v_cmp_eq_u32_e32 vcc, 0, v214
	s_and_saveexec_b64 s[98:99], vcc
	global_store_dword v210, v211, s[100:101]
	s_mov_b64 exec, s[98:99]
	s_add_u32 s88, s88, 0x10000
	s_addc_u32 s89, s89, 0
	s_add_u32 s100, s100, 0x400
	s_addc_u32 s101, s101, 0
	s_waitcnt vmcnt(22)
	v_fma_f32 v92, v92, 0.5, v184
	v_fma_f32 v93, v93, 0.5, v185
	v_fma_f32 v94, v94, 0.5, v186
	v_fma_f32 v95, v95, 0.5, v187
	global_store_dwordx4 v148, v[92:95], s[88:89]
	v_mul_f32_e32 v211, v92, v92
	v_fmac_f32_e32 v211, v93, v93
	v_fmac_f32_e32 v211, v94, v94
	v_fmac_f32_e32 v211, v95, v95
	global_load_dwordx4 v[184:187], v148, s[86:87] offset:64
	s_waitcnt vmcnt(23)
	v_fma_f32 v88, v88, 0.5, v188
	v_fma_f32 v89, v89, 0.5, v189
	v_fma_f32 v90, v90, 0.5, v190
	v_fma_f32 v91, v91, 0.5, v191
	global_store_dwordx4 v148, v[88:91], s[88:89] offset:64
	v_fmac_f32_e32 v211, v88, v88
	v_fmac_f32_e32 v211, v89, v89
	v_fmac_f32_e32 v211, v90, v90
	v_fmac_f32_e32 v211, v91, v91
	global_load_dwordx4 v[188:191], v148, s[86:87] offset:512
	s_waitcnt vmcnt(24)
	v_fma_f32 v84, v84, 0.5, v192
	v_fma_f32 v85, v85, 0.5, v193
	v_fma_f32 v86, v86, 0.5, v194
	v_fma_f32 v87, v87, 0.5, v195
	global_store_dwordx4 v148, v[84:87], s[88:89] offset:512
	v_fmac_f32_e32 v211, v84, v84
	v_fmac_f32_e32 v211, v85, v85
	v_fmac_f32_e32 v211, v86, v86
	v_fmac_f32_e32 v211, v87, v87
	global_load_dwordx4 v[192:195], v148, s[86:87] offset:576
	s_waitcnt vmcnt(25)
	v_fma_f32 v80, v80, 0.5, v196
	v_fma_f32 v81, v81, 0.5, v197
	v_fma_f32 v82, v82, 0.5, v198
	v_fma_f32 v83, v83, 0.5, v199
	global_store_dwordx4 v148, v[80:83], s[88:89] offset:576
	v_fmac_f32_e32 v211, v80, v80
	v_fmac_f32_e32 v211, v81, v81
	v_fmac_f32_e32 v211, v82, v82
	v_fmac_f32_e32 v211, v83, v83
	s_add_u32 s86, s86, 0x10000
	s_addc_u32 s87, s87, 0
	global_load_dwordx4 v[196:199], v148, s[86:87]
	s_nop 0
	ds_bpermute_b32 v215, v212, v211
	s_waitcnt lgkmcnt(0)
	v_add_f32_e32 v211, v211, v215
	s_nop 0
	ds_bpermute_b32 v215, v213, v211
	s_waitcnt lgkmcnt(0)
	v_add_f32_e32 v211, v211, v215
	v_cmp_eq_u32_e32 vcc, 0, v214
	s_and_saveexec_b64 s[98:99], vcc
	global_store_dword v210, v211, s[100:101]
	s_mov_b64 exec, s[98:99]
	s_add_u32 s88, s88, 0x10000
	s_addc_u32 s89, s89, 0
	s_add_u32 s100, s100, 0x400
	s_addc_u32 s101, s101, 0
	s_waitcnt vmcnt(27)
	v_fma_f32 v76, v76, 0.5, v200
	v_fma_f32 v77, v77, 0.5, v201
	v_fma_f32 v78, v78, 0.5, v202
	v_fma_f32 v79, v79, 0.5, v203
	global_store_dwordx4 v148, v[76:79], s[88:89]
	v_mul_f32_e32 v211, v76, v76
	v_fmac_f32_e32 v211, v77, v77
	v_fmac_f32_e32 v211, v78, v78
	v_fmac_f32_e32 v211, v79, v79
	global_load_dwordx4 v[200:203], v148, s[86:87] offset:64
	s_waitcnt vmcnt(27)
	v_fma_f32 v72, v72, 0.5, v144
	v_fma_f32 v73, v73, 0.5, v145
	v_fma_f32 v74, v74, 0.5, v146
	v_fma_f32 v75, v75, 0.5, v147
	global_store_dwordx4 v148, v[72:75], s[88:89] offset:64
	v_fmac_f32_e32 v211, v72, v72
	v_fmac_f32_e32 v211, v73, v73
	v_fmac_f32_e32 v211, v74, v74
	v_fmac_f32_e32 v211, v75, v75
	global_load_dwordx4 v[144:147], v148, s[86:87] offset:512
	s_waitcnt vmcnt(27)
	v_fma_f32 v68, v68, 0.5, v156
	v_fma_f32 v69, v69, 0.5, v157
	v_fma_f32 v70, v70, 0.5, v158
	v_fma_f32 v71, v71, 0.5, v159
	global_store_dwordx4 v148, v[68:71], s[88:89] offset:512
	v_fmac_f32_e32 v211, v68, v68
	v_fmac_f32_e32 v211, v69, v69
	v_fmac_f32_e32 v211, v70, v70
	v_fmac_f32_e32 v211, v71, v71
	global_load_dwordx4 v[156:159], v148, s[86:87] offset:576
	s_waitcnt vmcnt(27)
	v_fma_f32 v64, v64, 0.5, v160
	v_fma_f32 v65, v65, 0.5, v161
	v_fma_f32 v66, v66, 0.5, v162
	v_fma_f32 v67, v67, 0.5, v163
	global_store_dwordx4 v148, v[64:67], s[88:89] offset:576
	v_fmac_f32_e32 v211, v64, v64
	v_fmac_f32_e32 v211, v65, v65
	v_fmac_f32_e32 v211, v66, v66
	v_fmac_f32_e32 v211, v67, v67
	s_add_u32 s86, s86, 0x10000
	s_addc_u32 s87, s87, 0
	global_load_dwordx4 v[160:163], v148, s[86:87]
	s_nop 0
	ds_bpermute_b32 v215, v212, v211
	s_waitcnt lgkmcnt(0)
	v_add_f32_e32 v211, v211, v215
	s_nop 0
	ds_bpermute_b32 v215, v213, v211
	s_waitcnt lgkmcnt(0)
	v_add_f32_e32 v211, v211, v215
	v_cmp_eq_u32_e32 vcc, 0, v214
	s_and_saveexec_b64 s[98:99], vcc
	global_store_dword v210, v211, s[100:101]
	s_mov_b64 exec, s[98:99]
	s_add_u32 s88, s88, 0x50000
	s_addc_u32 s89, s89, 0
	s_add_u32 s100, s100, 0x1400
	s_addc_u32 s101, s101, 0
	s_waitcnt vmcnt(28)
	v_fma_f32 v60, v60, 0.5, v164
	v_fma_f32 v61, v61, 0.5, v165
	v_fma_f32 v62, v62, 0.5, v166
	v_fma_f32 v63, v63, 0.5, v167
	global_store_dwordx4 v148, v[60:63], s[88:89]
	v_mul_f32_e32 v211, v60, v60
	v_fmac_f32_e32 v211, v61, v61
	v_fmac_f32_e32 v211, v62, v62
	v_fmac_f32_e32 v211, v63, v63
	global_load_dwordx4 v[164:167], v148, s[86:87] offset:64
	s_waitcnt vmcnt(27)
	v_fma_f32 v56, v56, 0.5, v168
	v_fma_f32 v57, v57, 0.5, v169
	v_fma_f32 v58, v58, 0.5, v170
	v_fma_f32 v59, v59, 0.5, v171
	global_store_dwordx4 v148, v[56:59], s[88:89] offset:64
	v_fmac_f32_e32 v211, v56, v56
	v_fmac_f32_e32 v211, v57, v57
	v_fmac_f32_e32 v211, v58, v58
	v_fmac_f32_e32 v211, v59, v59
	global_load_dwordx4 v[168:171], v148, s[86:87] offset:512
	s_waitcnt vmcnt(27)
	v_fma_f32 v52, v52, 0.5, v172
	v_fma_f32 v53, v53, 0.5, v173
	v_fma_f32 v54, v54, 0.5, v174
	v_fma_f32 v55, v55, 0.5, v175
	global_store_dwordx4 v148, v[52:55], s[88:89] offset:512
	v_fmac_f32_e32 v211, v52, v52
	v_fmac_f32_e32 v211, v53, v53
	v_fmac_f32_e32 v211, v54, v54
	v_fmac_f32_e32 v211, v55, v55
	global_load_dwordx4 v[172:175], v148, s[86:87] offset:576
	s_waitcnt vmcnt(27)
	v_fma_f32 v48, v48, 0.5, v176
	v_fma_f32 v49, v49, 0.5, v177
	v_fma_f32 v50, v50, 0.5, v178
	v_fma_f32 v51, v51, 0.5, v179
	global_store_dwordx4 v148, v[48:51], s[88:89] offset:576
	v_fmac_f32_e32 v211, v48, v48
	v_fmac_f32_e32 v211, v49, v49
	v_fmac_f32_e32 v211, v50, v50
	v_fmac_f32_e32 v211, v51, v51
	s_nop 0
	ds_bpermute_b32 v215, v212, v211
	s_waitcnt lgkmcnt(0)
	v_add_f32_e32 v211, v211, v215
	s_nop 0
	ds_bpermute_b32 v215, v213, v211
	s_waitcnt lgkmcnt(0)
	v_add_f32_e32 v211, v211, v215
	v_cmp_eq_u32_e32 vcc, 0, v214
	s_and_saveexec_b64 s[98:99], vcc
	global_store_dword v210, v211, s[100:101]
	s_mov_b64 exec, s[98:99]
	s_add_u32 s88, s88, 0x10000
	s_addc_u32 s89, s89, 0
	s_add_u32 s100, s100, 0x400
	s_addc_u32 s101, s101, 0
	s_waitcnt vmcnt(27)
	v_fma_f32 v44, v44, 0.5, v180
	v_fma_f32 v45, v45, 0.5, v181
	v_fma_f32 v46, v46, 0.5, v182
	v_fma_f32 v47, v47, 0.5, v183
	global_store_dwordx4 v148, v[44:47], s[88:89]
	v_mul_f32_e32 v211, v44, v44
	v_fmac_f32_e32 v211, v45, v45
	v_fmac_f32_e32 v211, v46, v46
	v_fmac_f32_e32 v211, v47, v47
	s_waitcnt vmcnt(25)
	v_fma_f32 v40, v40, 0.5, v184
	v_fma_f32 v41, v41, 0.5, v185
	v_fma_f32 v42, v42, 0.5, v186
	v_fma_f32 v43, v43, 0.5, v187
	global_store_dwordx4 v148, v[40:43], s[88:89] offset:64
	v_fmac_f32_e32 v211, v40, v40
	v_fmac_f32_e32 v211, v41, v41
	v_fmac_f32_e32 v211, v42, v42
	v_fmac_f32_e32 v211, v43, v43
	s_waitcnt vmcnt(24)
	v_fma_f32 v36, v36, 0.5, v188
	v_fma_f32 v37, v37, 0.5, v189
	v_fma_f32 v38, v38, 0.5, v190
	v_fma_f32 v39, v39, 0.5, v191
	global_store_dwordx4 v148, v[36:39], s[88:89] offset:512
	v_fmac_f32_e32 v211, v36, v36
	v_fmac_f32_e32 v211, v37, v37
	v_fmac_f32_e32 v211, v38, v38
	v_fmac_f32_e32 v211, v39, v39
	s_waitcnt vmcnt(23)
	v_fma_f32 v32, v32, 0.5, v192
	v_fma_f32 v33, v33, 0.5, v193
	v_fma_f32 v34, v34, 0.5, v194
	v_fma_f32 v35, v35, 0.5, v195
	global_store_dwordx4 v148, v[32:35], s[88:89] offset:576
	v_fmac_f32_e32 v211, v32, v32
	v_fmac_f32_e32 v211, v33, v33
	v_fmac_f32_e32 v211, v34, v34
	v_fmac_f32_e32 v211, v35, v35
	s_nop 0
	ds_bpermute_b32 v215, v212, v211
	s_waitcnt lgkmcnt(0)
	v_add_f32_e32 v211, v211, v215
	s_nop 0
	ds_bpermute_b32 v215, v213, v211
	s_waitcnt lgkmcnt(0)
	v_add_f32_e32 v211, v211, v215
	v_cmp_eq_u32_e32 vcc, 0, v214
	s_and_saveexec_b64 s[98:99], vcc
	global_store_dword v210, v211, s[100:101]
	s_mov_b64 exec, s[98:99]
	s_add_u32 s88, s88, 0x10000
	s_addc_u32 s89, s89, 0
	s_add_u32 s100, s100, 0x400
	s_addc_u32 s101, s101, 0
	s_waitcnt vmcnt(23)
	v_fma_f32 v28, v28, 0.5, v196
	v_fma_f32 v29, v29, 0.5, v197
	v_fma_f32 v30, v30, 0.5, v198
	v_fma_f32 v31, v31, 0.5, v199
	global_store_dwordx4 v148, v[28:31], s[88:89]
	v_mul_f32_e32 v211, v28, v28
	v_fmac_f32_e32 v211, v29, v29
	v_fmac_f32_e32 v211, v30, v30
	v_fmac_f32_e32 v211, v31, v31
	s_waitcnt vmcnt(21)
	v_fma_f32 v24, v24, 0.5, v200
	v_fma_f32 v25, v25, 0.5, v201
	v_fma_f32 v26, v26, 0.5, v202
	v_fma_f32 v27, v27, 0.5, v203
	global_store_dwordx4 v148, v[24:27], s[88:89] offset:64
	v_fmac_f32_e32 v211, v24, v24
	v_fmac_f32_e32 v211, v25, v25
	v_fmac_f32_e32 v211, v26, v26
	v_fmac_f32_e32 v211, v27, v27
	s_waitcnt vmcnt(20)
	v_fma_f32 v20, v20, 0.5, v144
	v_fma_f32 v21, v21, 0.5, v145
	v_fma_f32 v22, v22, 0.5, v146
	v_fma_f32 v23, v23, 0.5, v147
	global_store_dwordx4 v148, v[20:23], s[88:89] offset:512
	v_fmac_f32_e32 v211, v20, v20
	v_fmac_f32_e32 v211, v21, v21
	v_fmac_f32_e32 v211, v22, v22
	v_fmac_f32_e32 v211, v23, v23
	s_waitcnt vmcnt(19)
	v_fma_f32 v16, v16, 0.5, v156
	v_fma_f32 v17, v17, 0.5, v157
	v_fma_f32 v18, v18, 0.5, v158
	v_fma_f32 v19, v19, 0.5, v159
	global_store_dwordx4 v148, v[16:19], s[88:89] offset:576
	v_fmac_f32_e32 v211, v16, v16
	v_fmac_f32_e32 v211, v17, v17
	v_fmac_f32_e32 v211, v18, v18
	v_fmac_f32_e32 v211, v19, v19
	s_nop 0
	ds_bpermute_b32 v215, v212, v211
	s_waitcnt lgkmcnt(0)
	v_add_f32_e32 v211, v211, v215
	s_nop 0
	ds_bpermute_b32 v215, v213, v211
	s_waitcnt lgkmcnt(0)
	v_add_f32_e32 v211, v211, v215
	v_cmp_eq_u32_e32 vcc, 0, v214
	s_and_saveexec_b64 s[98:99], vcc
	global_store_dword v210, v211, s[100:101]
	s_mov_b64 exec, s[98:99]
	s_add_u32 s88, s88, 0x10000
	s_addc_u32 s89, s89, 0
	s_add_u32 s100, s100, 0x400
	s_addc_u32 s101, s101, 0
	s_waitcnt vmcnt(19)
	v_fma_f32 v12, v12, 0.5, v160
	v_fma_f32 v13, v13, 0.5, v161
	v_fma_f32 v14, v14, 0.5, v162
	v_fma_f32 v15, v15, 0.5, v163
	global_store_dwordx4 v148, v[12:15], s[88:89]
	v_mul_f32_e32 v211, v12, v12
	v_fmac_f32_e32 v211, v13, v13
	v_fmac_f32_e32 v211, v14, v14
	v_fmac_f32_e32 v211, v15, v15
	s_waitcnt vmcnt(17)
	v_fma_f32 v8, v8, 0.5, v164
	v_fma_f32 v9, v9, 0.5, v165
	v_fma_f32 v10, v10, 0.5, v166
	v_fma_f32 v11, v11, 0.5, v167
	global_store_dwordx4 v148, v[8:11], s[88:89] offset:64
	v_fmac_f32_e32 v211, v8, v8
	v_fmac_f32_e32 v211, v9, v9
	v_fmac_f32_e32 v211, v10, v10
	v_fmac_f32_e32 v211, v11, v11
	s_waitcnt vmcnt(16)
	v_fma_f32 v4, v4, 0.5, v168
	v_fma_f32 v5, v5, 0.5, v169
	v_fma_f32 v6, v6, 0.5, v170
	v_fma_f32 v7, v7, 0.5, v171
	global_store_dwordx4 v148, v[4:7], s[88:89] offset:512
	v_fmac_f32_e32 v211, v4, v4
	v_fmac_f32_e32 v211, v5, v5
	v_fmac_f32_e32 v211, v6, v6
	v_fmac_f32_e32 v211, v7, v7
	s_waitcnt vmcnt(15)
	v_fma_f32 v0, v0, 0.5, v172
	v_fma_f32 v1, v1, 0.5, v173
	v_fma_f32 v2, v2, 0.5, v174
	v_fma_f32 v3, v3, 0.5, v175
	global_store_dwordx4 v148, v[0:3], s[88:89] offset:576
	v_fmac_f32_e32 v211, v0, v0
	v_fmac_f32_e32 v211, v1, v1
	v_fmac_f32_e32 v211, v2, v2
	v_fmac_f32_e32 v211, v3, v3
	s_nop 0
	ds_bpermute_b32 v215, v212, v211
	s_waitcnt lgkmcnt(0)
	v_add_f32_e32 v211, v211, v215
	s_nop 0
	ds_bpermute_b32 v215, v213, v211
	s_waitcnt lgkmcnt(0)
	v_add_f32_e32 v211, v211, v215
	v_cmp_eq_u32_e32 vcc, 0, v214
	s_and_saveexec_b64 s[98:99], vcc
	global_store_dword v210, v211, s[100:101]
	s_mov_b64 exec, s[98:99]
	s_and_b64 vcc, exec, s[8:9]
	s_mov_b64 s[8:9], -1
	s_cbranch_vccnz .LBB0_1477
	s_andn2_b64 vcc, exec, s[14:15]
	s_cbranch_vccnz .LBB0_1476
	s_barrier
	s_branch .LBB0_1476
